# row-max code: canonicalising v_max x,x pairs folded into the following v_max (14 sites, MLA + NA)
# speedup vs baseline: 1.0147x; 1.0026x over previous
; __device__ __forceinline__ float bf2f(unsigned h) { return __uint_as_float(h << 16); }
; __device__ __forceinline__ void mla_unit(char* lds, const bf16_t* __restrict__ Qp, const bf16_t* __restrict__ Knp, const bf16_t* __restrict__ Vp, ...
;     ...
;   const bf16_t* Qw = Qp + (long)(wid * QBLK + r32) * LDQ + hi * 8;
; #pragma unroll
;   for (int d0 = 0; d0 < 8; ++d0) { const u32x4 raw = *reinterpret_cast<const u32x4*>(Qw + d0 * 16); u32x4 w;
; #pragma unroll
;     for (int p = 0; p < 4; ++p) w[p] = cvtpk(bf2f(raw[p] & 0xffffu) * C, bf2f(raw[p] >> 16) * C);
;     qr[d0] = *reinterpret_cast<bf16x8*>(&w); }
;   { const int pos = pos0 + wid * QBLK + r32;
; #pragma unroll
;     for (int d0 = 0; d0 < 4; ++d0) {
;       const u32x4 raw = *reinterpret_cast<const u32x4*>(Qw + 128 + d0 * 16);
;       const int i0 = d0 * 8 + hi * 4;
;       const f32x4 cc = *reinterpret_cast<const f32x4*>(cs_tab + pos * 32 + i0) * C, ss = *reinterpret_cast<const f32x4*>(sn_tab + pos * 32 + i0) * C;
.LBB0_238:
	s_lshl_b32 s1, s74, 8
	s_lshl_b64 s[64:65], s[6:7], 13
	s_and_b32 s1, s1, 0x1f00
	s_or_b32 s64, s64, s1
	s_mul_hi_u32 s6, s64, 0x1800
	s_mul_i32 s7, s65, 0x1800
	s_mul_i32 s5, s64, 0x1800
	s_add_i32 s6, s6, s7
	v_readlane_b32 s7, v254, 60
	s_add_u32 s5, s7, s5
	v_readlane_b32 s7, v254, 61
	s_addc_u32 s7, s7, s6
	s_mul_i32 s6, s38, 0x180
	s_add_u32 s6, s5, s6
	s_addc_u32 s7, s7, 0
	v_and_b32_e32 v196, 31, v50
	s_lshl_b32 s39, s8, 5
	v_or_b32_e32 v1, s39, v196
	v_mov_b64_e32 v[2:3], s[6:7]
	s_movk_i32 s5, 0x1800
	v_mad_i64_i32 v[2:3], s[6:7], v1, s5, v[2:3]
	v_lshlrev_b32_e32 v194, 4, v49
	v_mov_b32_e32 v195, v0
	v_lshl_add_u64 v[2:3], v[2:3], 0, v[194:195]
	global_load_dwordx4 v[130:133], v[2:3], off
	global_load_dwordx4 v[134:137], v[2:3], off offset:32
	global_load_dwordx4 v[138:141], v[2:3], off offset:64
	global_load_dwordx4 v[142:145], v[2:3], off offset:96
	global_load_dwordx4 v[154:157], v[2:3], off offset:128
	global_load_dwordx4 v[150:153], v[2:3], off offset:160
	global_load_dwordx4 v[146:149], v[2:3], off offset:192
	global_load_dwordx4 v[158:161], v[2:3], off offset:224
	global_load_dwordx4 v[162:165], v[2:3], off offset:256
	global_load_dwordx4 v[166:169], v[2:3], off offset:288
	global_load_dwordx4 v[170:173], v[2:3], off offset:320
	global_load_dwordx4 v[174:177], v[2:3], off offset:352
	s_mov_b32 s6, 0x3dd53b94
	v_lshlrev_b32_e32 v204, 8, v196
	v_and_b32_e32 v51, 0xf0, v48
	v_add_u32_e32 v66, 0, v204
	s_waitcnt vmcnt(20)
	v_xad_u32 v56, v194, v51, v66
	v_lshlrev_b32_e32 v205, 7, v196
	s_and_b32 s0, s0, 0x3fffffc0
	s_lshl_b32 s0, s0, 2
	s_add_i32 s33, s0, 0
	s_add_i32 s33, s33, 0x1e000
	v_lshl_add_u32 v200, v196, 2, s33
	s_waitcnt vmcnt(11)
	v_lshlrev_b32_e32 v1, 16, v130
	v_and_b32_e32 v4, 0xffff0000, v130
	v_lshlrev_b32_e32 v8, 16, v131
	v_and_b32_e32 v5, 0xffff0000, v131
	v_lshlrev_b32_e32 v9, 16, v132
	v_and_b32_e32 v6, 0xffff0000, v132
	v_lshlrev_b32_e32 v10, 16, v133
	v_and_b32_e32 v7, 0xffff0000, v133
	v_mul_f32_e32 v4, 0x3dd53b94, v4
	v_mul_f32_e32 v5, 0x3dd53b94, v5
	v_mul_f32_e32 v6, 0x3dd53b94, v6
	v_mul_f32_e32 v7, 0x3dd53b94, v7
	v_mul_f32_e32 v1, 0x3dd53b94, v1
	v_mul_f32_e32 v8, 0x3dd53b94, v8
	v_mul_f32_e32 v9, 0x3dd53b94, v9
	v_mul_f32_e32 v10, 0x3dd53b94, v10
	v_cvt_pk_bf16_f32 v130, v1, v4
	v_cvt_pk_bf16_f32 v131, v8, v5
	v_cvt_pk_bf16_f32 v132, v9, v6
	v_cvt_pk_bf16_f32 v133, v10, v7
	s_waitcnt vmcnt(10)
	v_lshlrev_b32_e32 v1, 16, v134
	v_and_b32_e32 v4, 0xffff0000, v134
	v_lshlrev_b32_e32 v8, 16, v135
	v_and_b32_e32 v5, 0xffff0000, v135
	v_lshlrev_b32_e32 v9, 16, v136
	v_and_b32_e32 v6, 0xffff0000, v136
	v_lshlrev_b32_e32 v10, 16, v137
	v_and_b32_e32 v7, 0xffff0000, v137
	v_mul_f32_e32 v4, 0x3dd53b94, v4
	v_mul_f32_e32 v5, 0x3dd53b94, v5
	v_mul_f32_e32 v6, 0x3dd53b94, v6
	v_mul_f32_e32 v7, 0x3dd53b94, v7
	v_mul_f32_e32 v1, 0x3dd53b94, v1
	v_mul_f32_e32 v8, 0x3dd53b94, v8
	v_mul_f32_e32 v9, 0x3dd53b94, v9
	v_mul_f32_e32 v10, 0x3dd53b94, v10
	v_cvt_pk_bf16_f32 v134, v1, v4
	v_cvt_pk_bf16_f32 v135, v8, v5
	v_cvt_pk_bf16_f32 v136, v9, v6
	v_cvt_pk_bf16_f32 v137, v10, v7
	s_waitcnt vmcnt(9)
	v_lshlrev_b32_e32 v1, 16, v138
	v_and_b32_e32 v4, 0xffff0000, v138
	v_lshlrev_b32_e32 v8, 16, v139
	v_and_b32_e32 v5, 0xffff0000, v139
	v_lshlrev_b32_e32 v9, 16, v140
	v_and_b32_e32 v6, 0xffff0000, v140
	v_lshlrev_b32_e32 v10, 16, v141
	v_and_b32_e32 v7, 0xffff0000, v141
	v_mul_f32_e32 v4, 0x3dd53b94, v4
	v_mul_f32_e32 v5, 0x3dd53b94, v5
	v_mul_f32_e32 v6, 0x3dd53b94, v6
	v_mul_f32_e32 v7, 0x3dd53b94, v7
	v_mul_f32_e32 v1, 0x3dd53b94, v1
	v_mul_f32_e32 v8, 0x3dd53b94, v8
	v_mul_f32_e32 v9, 0x3dd53b94, v9
	v_mul_f32_e32 v10, 0x3dd53b94, v10
	v_cvt_pk_bf16_f32 v138, v1, v4
	v_cvt_pk_bf16_f32 v139, v8, v5
	v_cvt_pk_bf16_f32 v140, v9, v6
	v_cvt_pk_bf16_f32 v141, v10, v7
	s_waitcnt vmcnt(8)
	v_lshlrev_b32_e32 v1, 16, v142
	v_and_b32_e32 v4, 0xffff0000, v142
	v_lshlrev_b32_e32 v8, 16, v143
	v_and_b32_e32 v5, 0xffff0000, v143
	v_lshlrev_b32_e32 v9, 16, v144
	v_and_b32_e32 v6, 0xffff0000, v144
	v_lshlrev_b32_e32 v10, 16, v145
	v_and_b32_e32 v7, 0xffff0000, v145
	v_mul_f32_e32 v4, 0x3dd53b94, v4
	v_mul_f32_e32 v5, 0x3dd53b94, v5
	v_mul_f32_e32 v6, 0x3dd53b94, v6
	v_mul_f32_e32 v7, 0x3dd53b94, v7
	v_mul_f32_e32 v1, 0x3dd53b94, v1
	v_mul_f32_e32 v8, 0x3dd53b94, v8
	v_mul_f32_e32 v9, 0x3dd53b94, v9
	v_mul_f32_e32 v10, 0x3dd53b94, v10
	v_cvt_pk_bf16_f32 v142, v1, v4
	v_cvt_pk_bf16_f32 v143, v8, v5
	v_cvt_pk_bf16_f32 v144, v9, v6
	v_cvt_pk_bf16_f32 v145, v10, v7
	s_waitcnt vmcnt(7)
	v_lshlrev_b32_e32 v1, 16, v154
	v_and_b32_e32 v4, 0xffff0000, v154
	v_lshlrev_b32_e32 v8, 16, v155
	v_and_b32_e32 v5, 0xffff0000, v155
	v_lshlrev_b32_e32 v9, 16, v156
	v_and_b32_e32 v6, 0xffff0000, v156
	v_lshlrev_b32_e32 v10, 16, v157
	v_and_b32_e32 v7, 0xffff0000, v157
	v_mul_f32_e32 v4, 0x3dd53b94, v4
	v_mul_f32_e32 v5, 0x3dd53b94, v5
	v_mul_f32_e32 v6, 0x3dd53b94, v6
	v_mul_f32_e32 v7, 0x3dd53b94, v7
	v_mul_f32_e32 v1, 0x3dd53b94, v1
	v_mul_f32_e32 v8, 0x3dd53b94, v8
	v_mul_f32_e32 v9, 0x3dd53b94, v9
	v_mul_f32_e32 v10, 0x3dd53b94, v10
	v_cvt_pk_bf16_f32 v154, v1, v4
	v_cvt_pk_bf16_f32 v155, v8, v5
	v_cvt_pk_bf16_f32 v156, v9, v6
	v_cvt_pk_bf16_f32 v157, v10, v7
	s_waitcnt vmcnt(6)
	v_lshlrev_b32_e32 v1, 16, v150
	v_and_b32_e32 v4, 0xffff0000, v150
	v_lshlrev_b32_e32 v8, 16, v151
	v_and_b32_e32 v5, 0xffff0000, v151
	v_lshlrev_b32_e32 v9, 16, v152
	v_and_b32_e32 v6, 0xffff0000, v152
	v_lshlrev_b32_e32 v10, 16, v153
	v_and_b32_e32 v7, 0xffff0000, v153
	v_mul_f32_e32 v4, 0x3dd53b94, v4
	v_mul_f32_e32 v5, 0x3dd53b94, v5
	v_mul_f32_e32 v6, 0x3dd53b94, v6
	v_mul_f32_e32 v7, 0x3dd53b94, v7
	v_mul_f32_e32 v1, 0x3dd53b94, v1
	v_mul_f32_e32 v8, 0x3dd53b94, v8
	v_mul_f32_e32 v9, 0x3dd53b94, v9
	v_mul_f32_e32 v10, 0x3dd53b94, v10
	v_cvt_pk_bf16_f32 v150, v1, v4
	v_cvt_pk_bf16_f32 v151, v8, v5
	v_cvt_pk_bf16_f32 v152, v9, v6
	v_cvt_pk_bf16_f32 v153, v10, v7
	s_waitcnt vmcnt(5)
; __device__ __forceinline__ float bf2f(unsigned h) { return __uint_as_float(h << 16); }
; __device__ __forceinline__ void mla_unit(char* lds, const bf16_t* __restrict__ Qp, const bf16_t* __restrict__ Knp, const bf16_t* __restrict__ Vp, ...
;     ...
;   { const int pos = pos0 + wid * QBLK + r32;
; #pragma unroll
;     for (int d0 = 0; d0 < 4; ++d0) {
;       const u32x4 raw = *reinterpret_cast<const u32x4*>(Qw + 128 + d0 * 16);
;       const int i0 = d0 * 8 + hi * 4;
;       const f32x4 cc = *reinterpret_cast<const f32x4*>(cs_tab + pos * 32 + i0) * C, ss = *reinterpret_cast<const f32x4*>(sn_tab + pos * 32 + i0) * C;
;       u32x4 w;
; #pragma unroll
;       for (int p = 0; p < 4; ++p) { const float x1 = bf2f(raw[p] & 0xffffu), x2 = bf2f(raw[p] >> 16); w[p] = cvtpk(x1 * cc[p] - x2 * ss[p], x1 * ss[p] + x2 * cc[p]); }
;       qr[8 + d0] = *reinterpret_cast<bf16x8*>(&w);
;     } }
	v_lshlrev_b32_e32 v8, 16, v147
	v_lshlrev_b32_e32 v9, 16, v148
	v_and_b32_e32 v6, 0xffff0000, v148
	v_lshlrev_b32_e32 v10, 16, v149
	v_and_b32_e32 v7, 0xffff0000, v149
	v_lshlrev_b32_e32 v1, 16, v146
	v_and_b32_e32 v4, 0xffff0000, v146
	v_and_b32_e32 v5, 0xffff0000, v147
	v_mul_f32_e32 v8, 0x3dd53b94, v8
	v_mul_f32_e32 v9, 0x3dd53b94, v9
	v_mul_f32_e32 v6, 0x3dd53b94, v6
	v_mul_f32_e32 v7, 0x3dd53b94, v7
	v_mul_f32_e32 v1, 0x3dd53b94, v1
	v_mul_f32_e32 v4, 0x3dd53b94, v4
	v_mul_f32_e32 v5, 0x3dd53b94, v5
	v_mul_f32_e32 v10, 0x3dd53b94, v10
	v_cvt_pk_bf16_f32 v146, v1, v4
	v_cvt_pk_bf16_f32 v147, v8, v5
	v_cvt_pk_bf16_f32 v148, v9, v6
	v_cvt_pk_bf16_f32 v149, v10, v7
	v_or_b32_e32 v1, s1, v196
	v_add_lshl_u32 v4, v1, s39, 5
	v_ashrrev_i32_e32 v5, 31, v4
	v_lshlrev_b64 v[4:5], 2, v[4:5]
	v_lshl_add_u64 v[10:11], s[34:35], 0, v[4:5]
	v_lshl_add_u64 v[12:13], s[86:87], 0, v[4:5]
	v_lshl_add_u64 v[4:5], v[10:11], 0, v[194:195]
	v_lshl_add_u64 v[18:19], v[12:13], 0, v[194:195]
	s_add_i32 s1, 0, 0x18000
	v_add_u32_e32 v206, s1, v205
	s_waitcnt vmcnt(4)
	v_lshlrev_b32_e32 v1, 16, v158
	v_and_b32_e32 v6, 0xffff0000, v158
	v_lshlrev_b32_e32 v10, 16, v159
	v_and_b32_e32 v7, 0xffff0000, v159
	v_lshlrev_b32_e32 v11, 16, v160
	v_and_b32_e32 v8, 0xffff0000, v160
	v_lshlrev_b32_e32 v14, 16, v161
	v_and_b32_e32 v9, 0xffff0000, v161
	v_mul_f32_e32 v6, 0x3dd53b94, v6
	v_mul_f32_e32 v10, 0x3dd53b94, v10
	v_mul_f32_e32 v7, 0x3dd53b94, v7
	v_mul_f32_e32 v11, 0x3dd53b94, v11
	v_mul_f32_e32 v8, 0x3dd53b94, v8
	v_mul_f32_e32 v14, 0x3dd53b94, v14
	v_mul_f32_e32 v9, 0x3dd53b94, v9
	v_mul_f32_e32 v1, 0x3dd53b94, v1
	v_cvt_pk_bf16_f32 v158, v1, v6
	v_cvt_pk_bf16_f32 v159, v10, v7
	v_cvt_pk_bf16_f32 v160, v11, v8
	v_cvt_pk_bf16_f32 v161, v14, v9
	global_load_dwordx4 v[10:13], v[4:5], off
	global_load_dwordx4 v[14:17], v[18:19], off
	s_waitcnt vmcnt(1)
	v_mov_b32_e32 v22, v10
	s_waitcnt vmcnt(0)
	v_mov_b32_e32 v23, v14
	v_mov_b32_e32 v14, v11
	v_mov_b32_e32 v24, v12
	v_mov_b32_e32 v25, v16
	v_mov_b32_e32 v16, v13
	v_lshlrev_b32_e32 v20, 16, v162
	v_and_b32_e32 v21, 0xffff0000, v162
	v_lshlrev_b32_e32 v6, 16, v163
	v_and_b32_e32 v7, 0xffff0000, v163
	v_lshlrev_b32_e32 v10, 16, v164
	v_and_b32_e32 v11, 0xffff0000, v164
	v_lshlrev_b32_e32 v8, 16, v165
	v_and_b32_e32 v9, 0xffff0000, v165
	v_pk_mul_f32 v[12:13], v[22:23], s[6:7] op_sel_hi:[1,0]
	v_pk_mul_f32 v[14:15], v[14:15], s[6:7] op_sel_hi:[1,0]
	v_pk_mul_f32 v[22:23], v[24:25], s[6:7] op_sel_hi:[1,0]
	v_pk_mul_f32 v[16:17], v[16:17], s[6:7] op_sel_hi:[1,0]
	v_pk_mul_f32 v[24:25], v[12:13], v[20:21]
	v_pk_mul_f32 v[12:13], v[12:13], v[20:21] op_sel:[0,1] op_sel_hi:[1,0]
	v_pk_mul_f32 v[20:21], v[14:15], v[6:7]
	v_pk_mul_f32 v[6:7], v[14:15], v[6:7] op_sel:[0,1] op_sel_hi:[1,0]
	v_pk_mul_f32 v[14:15], v[22:23], v[10:11]
	v_pk_mul_f32 v[10:11], v[22:23], v[10:11] op_sel:[0,1] op_sel_hi:[1,0]
	v_pk_mul_f32 v[22:23], v[16:17], v[8:9]
	v_pk_mul_f32 v[8:9], v[16:17], v[8:9] op_sel:[0,1] op_sel_hi:[1,0]
	v_add_f32_e32 v12, v12, v13
	v_sub_f32_e32 v13, v20, v21
	v_add_f32_e32 v6, v6, v7
	v_sub_f32_e32 v7, v14, v15
	v_add_f32_e32 v10, v10, v11
	v_sub_f32_e32 v11, v22, v23
	v_add_f32_e32 v8, v8, v9
	v_sub_f32_e32 v1, v24, v25
	v_cvt_pk_bf16_f32 v162, v1, v12
	v_cvt_pk_bf16_f32 v163, v13, v6
	v_cvt_pk_bf16_f32 v164, v7, v10
	v_cvt_pk_bf16_f32 v165, v11, v8
	global_load_dwordx4 v[10:13], v[4:5], off offset:32
	global_load_dwordx4 v[14:17], v[18:19], off offset:32
	s_waitcnt vmcnt(2)
	v_lshlrev_b32_e32 v20, 16, v166
	s_waitcnt vmcnt(1)
	v_mov_b32_e32 v22, v10
	s_waitcnt vmcnt(0)
	v_mov_b32_e32 v23, v14
	v_mov_b32_e32 v14, v11
	v_mov_b32_e32 v24, v12
	v_mov_b32_e32 v25, v16
	v_mov_b32_e32 v16, v13
	v_and_b32_e32 v21, 0xffff0000, v166
	v_lshlrev_b32_e32 v6, 16, v167
	v_and_b32_e32 v7, 0xffff0000, v167
	v_lshlrev_b32_e32 v10, 16, v168
	v_and_b32_e32 v11, 0xffff0000, v168
	v_lshlrev_b32_e32 v8, 16, v169
	v_and_b32_e32 v9, 0xffff0000, v169
	v_pk_mul_f32 v[12:13], v[22:23], s[6:7] op_sel_hi:[1,0]
	v_pk_mul_f32 v[14:15], v[14:15], s[6:7] op_sel_hi:[1,0]
	v_pk_mul_f32 v[22:23], v[24:25], s[6:7] op_sel_hi:[1,0]
	v_pk_mul_f32 v[16:17], v[16:17], s[6:7] op_sel_hi:[1,0]
	v_pk_mul_f32 v[24:25], v[12:13], v[20:21]
	v_pk_mul_f32 v[12:13], v[12:13], v[20:21] op_sel:[0,1] op_sel_hi:[1,0]
	v_pk_mul_f32 v[20:21], v[14:15], v[6:7]
	v_pk_mul_f32 v[6:7], v[14:15], v[6:7] op_sel:[0,1] op_sel_hi:[1,0]
	v_pk_mul_f32 v[14:15], v[22:23], v[10:11]
	v_pk_mul_f32 v[10:11], v[22:23], v[10:11] op_sel:[0,1] op_sel_hi:[1,0]
	v_pk_mul_f32 v[22:23], v[16:17], v[8:9]
	v_pk_mul_f32 v[8:9], v[16:17], v[8:9] op_sel:[0,1] op_sel_hi:[1,0]
	v_add_f32_e32 v12, v12, v13
	v_sub_f32_e32 v13, v20, v21
	v_add_f32_e32 v6, v6, v7
	v_sub_f32_e32 v7, v14, v15
	v_add_f32_e32 v10, v10, v11
	v_sub_f32_e32 v11, v22, v23
	v_add_f32_e32 v8, v8, v9
	v_sub_f32_e32 v1, v24, v25
	v_cvt_pk_bf16_f32 v166, v1, v12
	v_cvt_pk_bf16_f32 v167, v13, v6
	v_cvt_pk_bf16_f32 v168, v7, v10
	v_cvt_pk_bf16_f32 v169, v11, v8
	global_load_dwordx4 v[10:13], v[4:5], off offset:64
	global_load_dwordx4 v[14:17], v[18:19], off offset:64
	s_waitcnt vmcnt(2)
	v_lshlrev_b32_e32 v20, 16, v170
	s_waitcnt vmcnt(1)
	v_mov_b32_e32 v22, v10
	s_waitcnt vmcnt(0)
; __device__ __forceinline__ float bf2f(unsigned h) { return __uint_as_float(h << 16); }
; __device__ __forceinline__ void qkt192n(f32x16& p0, f32x16& p1, const char* Ks, const char* Kr, const bf16x8* qr, const f32x16& negm, int r32, int hi) {
; #pragma unroll
;   for (int d0 = 0; d0 < 8; ++d0) { const int cb = d0 * 32 + hi * 16;
;     const bf16x8 b0 = *reinterpret_cast<const bf16x8*>(Ks + KSWZ(r32, cb));
;     const bf16x8 b1 = *reinterpret_cast<const bf16x8*>(Ks + KSWZ(32 + r32, cb));
;     if (d0 == 0) { p0 = __builtin_amdgcn_mfma_f32_32x32x16_bf16(b0, qr[0], negm, 0, 0, 0); p1 = __builtin_amdgcn_mfma_f32_32x32x16_bf16(b1, qr[0], negm, 0, 0, 0); }
;     else { p0 = __builtin_amdgcn_mfma_f32_32x32x16_bf16(b0, qr[d0], p0, 0, 0, 0); p1 = __builtin_amdgcn_mfma_f32_32x32x16_bf16(b1, qr[d0], p1, 0, 0, 0); } }
; __device__ __forceinline__ void mla_unit(char* lds, const bf16_t* __restrict__ Qp, const bf16_t* __restrict__ Knp, const bf16_t* __restrict__ Vp, ...
;     ...
;       for (int p = 0; p < 4; ++p) { const float x1 = bf2f(raw[p] & 0xffffu), x2 = bf2f(raw[p] >> 16); w[p] = cvtpk(x1 * cc[p] - x2 * ss[p], x1 * ss[p] + x2 * cc[p]); }
;       qr[8 + d0] = *reinterpret_cast<bf16x8*>(&w);
;     } }
;   f32x16 pA0, pA1, pB0, pB1; bf16x8 pa0, pa1, pa2, pa3;
;   constexpr float THRL = THR * 1.4426950408889634f;
;   float mhat = 0.f; f32x16 negm = f32x16{}; asm volatile("" : "+v"(negm));
	v_mov_b32_e32 v23, v14
	v_mov_b32_e32 v14, v11
	v_mov_b32_e32 v24, v12
	v_mov_b32_e32 v25, v16
	v_mov_b32_e32 v16, v13
	v_and_b32_e32 v21, 0xffff0000, v170
	v_lshlrev_b32_e32 v6, 16, v171
	v_and_b32_e32 v7, 0xffff0000, v171
	v_lshlrev_b32_e32 v10, 16, v172
	v_and_b32_e32 v11, 0xffff0000, v172
	v_lshlrev_b32_e32 v8, 16, v173
	v_and_b32_e32 v9, 0xffff0000, v173
	v_pk_mul_f32 v[12:13], v[22:23], s[6:7] op_sel_hi:[1,0]
	v_pk_mul_f32 v[14:15], v[14:15], s[6:7] op_sel_hi:[1,0]
	v_pk_mul_f32 v[22:23], v[24:25], s[6:7] op_sel_hi:[1,0]
	v_pk_mul_f32 v[16:17], v[16:17], s[6:7] op_sel_hi:[1,0]
	v_pk_mul_f32 v[24:25], v[12:13], v[20:21]
	v_pk_mul_f32 v[12:13], v[12:13], v[20:21] op_sel:[0,1] op_sel_hi:[1,0]
	v_pk_mul_f32 v[20:21], v[14:15], v[6:7]
	v_pk_mul_f32 v[6:7], v[14:15], v[6:7] op_sel:[0,1] op_sel_hi:[1,0]
	v_pk_mul_f32 v[14:15], v[22:23], v[10:11]
	v_pk_mul_f32 v[10:11], v[22:23], v[10:11] op_sel:[0,1] op_sel_hi:[1,0]
	v_pk_mul_f32 v[22:23], v[16:17], v[8:9]
	v_pk_mul_f32 v[8:9], v[16:17], v[8:9] op_sel:[0,1] op_sel_hi:[1,0]
	v_sub_f32_e32 v1, v24, v25
	v_add_f32_e32 v12, v12, v13
	v_sub_f32_e32 v13, v20, v21
	v_add_f32_e32 v6, v6, v7
	v_sub_f32_e32 v7, v14, v15
	v_add_f32_e32 v10, v10, v11
	v_sub_f32_e32 v11, v22, v23
	v_add_f32_e32 v8, v8, v9
	v_cvt_pk_bf16_f32 v170, v1, v12
	v_cvt_pk_bf16_f32 v171, v13, v6
	v_cvt_pk_bf16_f32 v172, v7, v10
	v_cvt_pk_bf16_f32 v173, v11, v8
	global_load_dwordx4 v[36:39], v[4:5], off offset:96
	global_load_dwordx4 v[40:43], v[18:19], off offset:96
	v_mov_b32_e32 v14, v0
	v_mov_b32_e32 v15, v0
	v_mov_b32_e32 v1, v0
	v_mov_b32_e32 v2, v0
	v_mov_b32_e32 v3, v0
	v_mov_b32_e32 v4, v0
	v_mov_b32_e32 v5, v0
	v_mov_b32_e32 v6, v0
	v_mov_b32_e32 v7, v0
	v_mov_b32_e32 v8, v0
	v_mov_b32_e32 v9, v0
	v_mov_b32_e32 v10, v0
	v_mov_b32_e32 v11, v0
	v_mov_b32_e32 v12, v0
	v_mov_b32_e32 v13, v0
	v_mov_b64_e32 v[30:31], v[14:15]
	v_mov_b64_e32 v[28:29], v[12:13]
	v_mov_b64_e32 v[26:27], v[10:11]
	v_mov_b64_e32 v[24:25], v[8:9]
	v_mov_b64_e32 v[22:23], v[6:7]
	v_mov_b64_e32 v[20:21], v[4:5]
	v_mov_b64_e32 v[18:19], v[2:3]
	v_mov_b64_e32 v[16:17], v[0:1]
	s_waitcnt vmcnt(2)
	v_lshlrev_b32_e32 v44, 16, v174
	s_waitcnt vmcnt(1)
	v_mov_b32_e32 v46, v36
	s_waitcnt vmcnt(0)
	v_mov_b32_e32 v47, v40
	v_mov_b32_e32 v40, v37
	v_mov_b32_e32 v52, v38
	v_mov_b32_e32 v53, v42
	v_mov_b32_e32 v42, v39
	v_and_b32_e32 v45, 0xffff0000, v174
	v_lshlrev_b32_e32 v32, 16, v175
	v_and_b32_e32 v33, 0xffff0000, v175
	v_lshlrev_b32_e32 v36, 16, v176
	v_and_b32_e32 v37, 0xffff0000, v176
	v_lshlrev_b32_e32 v34, 16, v177
	v_and_b32_e32 v35, 0xffff0000, v177
	v_pk_mul_f32 v[38:39], v[46:47], s[6:7] op_sel_hi:[1,0]
	v_pk_mul_f32 v[40:41], v[40:41], s[6:7] op_sel_hi:[1,0]
	v_pk_mul_f32 v[46:47], v[52:53], s[6:7] op_sel_hi:[1,0]
	v_pk_mul_f32 v[42:43], v[42:43], s[6:7] op_sel_hi:[1,0]
	v_pk_mul_f32 v[52:53], v[38:39], v[44:45]
	v_pk_mul_f32 v[38:39], v[38:39], v[44:45] op_sel:[0,1] op_sel_hi:[1,0]
	v_pk_mul_f32 v[44:45], v[40:41], v[32:33]
	v_pk_mul_f32 v[32:33], v[40:41], v[32:33] op_sel:[0,1] op_sel_hi:[1,0]
	v_pk_mul_f32 v[40:41], v[46:47], v[36:37]
	v_pk_mul_f32 v[36:37], v[46:47], v[36:37] op_sel:[0,1] op_sel_hi:[1,0]
	v_pk_mul_f32 v[46:47], v[42:43], v[34:35]
	v_pk_mul_f32 v[34:35], v[42:43], v[34:35] op_sel:[0,1] op_sel_hi:[1,0]
	v_sub_f32_e32 v42, v52, v53
	v_add_f32_e32 v38, v38, v39
	v_sub_f32_e32 v39, v44, v45
	v_add_f32_e32 v32, v32, v33
	v_sub_f32_e32 v33, v40, v41
	v_add_f32_e32 v36, v36, v37
	v_sub_f32_e32 v37, v46, v47
	v_add_f32_e32 v34, v34, v35
	v_cvt_pk_bf16_f32 v174, v42, v38
	v_cvt_pk_bf16_f32 v175, v39, v32
	v_cvt_pk_bf16_f32 v176, v33, v36
	v_cvt_pk_bf16_f32 v177, v37, v34
	s_waitcnt vmcnt(10) lgkmcnt(0)
	s_barrier
	ds_read_b128 v[52:55], v56 offset:49152
	ds_read_b128 v[56:59], v56 offset:57344
	s_waitcnt lgkmcnt(1)
	v_mfma_f32_32x32x16_bf16 v[32:47], v[52:55], v[130:133], v[16:31]
	v_or_b32_e32 v52, 32, v194
	v_xad_u32 v53, v52, v51, v66
	s_waitcnt lgkmcnt(0)
	v_mfma_f32_32x32x16_bf16 v[16:31], v[56:59], v[130:133], v[16:31]
	ds_read_b128 v[54:57], v53 offset:49152
	ds_read_b128 v[58:61], v53 offset:57344
	v_or_b32_e32 v53, 64, v194
	v_xad_u32 v62, v53, v51, v66
	s_waitcnt lgkmcnt(1)
	v_mfma_f32_32x32x16_bf16 v[32:47], v[54:57], v[134:137], v[32:47]
	s_waitcnt lgkmcnt(0)
	v_mfma_f32_32x32x16_bf16 v[16:31], v[58:61], v[134:137], v[16:31]
	ds_read_b128 v[54:57], v62 offset:49152
	ds_read_b128 v[58:61], v62 offset:57344
	s_waitcnt lgkmcnt(1)
	v_mfma_f32_32x32x16_bf16 v[32:47], v[54:57], v[138:141], v[32:47]
	v_or_b32_e32 v54, 0x60, v194
	v_xad_u32 v55, v54, v51, v66
	s_waitcnt lgkmcnt(0)
	v_mfma_f32_32x32x16_bf16 v[16:31], v[58:61], v[138:141], v[16:31]
	ds_read_b128 v[56:59], v55 offset:49152
	ds_read_b128 v[60:63], v55 offset:57344
	v_or_b32_e32 v55, 0x80, v194
	v_xad_u32 v64, v55, v51, v66
	s_waitcnt lgkmcnt(1)
	v_mfma_f32_32x32x16_bf16 v[32:47], v[56:59], v[142:145], v[32:47]
	s_waitcnt lgkmcnt(0)
	v_mfma_f32_32x32x16_bf16 v[16:31], v[60:63], v[142:145], v[16:31]
	ds_read_b128 v[56:59], v64 offset:49152
	ds_read_b128 v[60:63], v64 offset:57344
	s_waitcnt lgkmcnt(1)
	v_mfma_f32_32x32x16_bf16 v[32:47], v[56:59], v[154:157], v[32:47]
	v_or_b32_e32 v56, 0xa0, v194
	v_xad_u32 v57, v56, v51, v66
	s_waitcnt lgkmcnt(0)
	v_mfma_f32_32x32x16_bf16 v[16:31], v[60:63], v[154:157], v[16:31]
	ds_read_b128 v[58:61], v57 offset:49152
	ds_read_b128 v[62:65], v57 offset:57344
	v_or_b32_e32 v57, 0xc0, v194
	v_xad_u32 v67, v57, v51, v66
	s_waitcnt lgkmcnt(1)
	v_mfma_f32_32x32x16_bf16 v[32:47], v[58:61], v[150:153], v[32:47]
	s_waitcnt lgkmcnt(0)
	v_mfma_f32_32x32x16_bf16 v[16:31], v[62:65], v[150:153], v[16:31]
	ds_read_b128 v[58:61], v67 offset:49152
	ds_read_b128 v[62:65], v67 offset:57344
	s_waitcnt lgkmcnt(1)
; #define MX3(a, b, c) __builtin_fmaxf(__builtin_fmaxf((a), (b)), (c))
; #define MX3(a, b, c) __builtin_fmaxf(__builtin_fmaxf((a), (b)), (c))
; __device__ __forceinline__ float rowmax32(const f32x16& p0, const f32x16& p1) {
;   float a = MX3(p0[0], p0[1], p1[0]), b = MX3(p0[2], p0[3], p1[1]); a = MX3(a, p1[2], p1[3]);
; #pragma unroll
;   for (int r = 4; r < 16; r += 4) { a = MX3(a, p0[r], p0[r + 1]); b = MX3(b, p0[r + 2], p0[r + 3]); a = MX3(a, p1[r], p1[r + 1]); b = MX3(b, p1[r + 2], p1[r + 3]); }
;   float m = __builtin_fmaxf(a, b);
;   auto rr = __builtin_amdgcn_permlane32_swap(__float_as_uint(m), __float_as_uint(m), false, false);
;   return __builtin_fmaxf(__uint_as_float(rr[0]), __uint_as_float(rr[1]));
; }
	v_mfma_f32_32x32x16_bf16 v[32:47], v[58:61], v[146:149], v[32:47]
	v_or_b32_e32 v58, 0xe0, v194
	v_xad_u32 v59, v58, v51, v66
	s_waitcnt lgkmcnt(0)
	v_mfma_f32_32x32x16_bf16 v[16:31], v[62:65], v[146:149], v[16:31]
	ds_read_b128 v[60:63], v59 offset:49152
	ds_read_b128 v[64:67], v59 offset:57344
	v_lshlrev_b32_e32 v59, 3, v50
	v_and_b32_e32 v68, 0x70, v59
	v_xad_u32 v69, v194, v68, v206
	v_and_b32_e32 v50, 63, v50
	v_cmp_gt_u32_e64 s[40:41], 32, v50
	s_waitcnt lgkmcnt(1)
	v_mfma_f32_32x32x16_bf16 v[32:47], v[60:63], v[158:161], v[32:47]
	s_waitcnt lgkmcnt(0)
	v_mfma_f32_32x32x16_bf16 v[16:31], v[64:67], v[158:161], v[16:31]
	ds_read_b128 v[60:63], v69
	ds_read_b128 v[64:67], v69 offset:4096
	v_xad_u32 v69, v52, v68, v206
	s_waitcnt lgkmcnt(1)
	v_mfma_f32_32x32x16_bf16 v[32:47], v[60:63], v[162:165], v[32:47]
	s_waitcnt lgkmcnt(0)
	v_mfma_f32_32x32x16_bf16 v[16:31], v[64:67], v[162:165], v[16:31]
	ds_read_b128 v[60:63], v69
	ds_read_b128 v[64:67], v69 offset:4096
	v_xad_u32 v69, v53, v68, v206
	v_xad_u32 v68, v54, v68, v206
	s_waitcnt lgkmcnt(1)
	v_mfma_f32_32x32x16_bf16 v[32:47], v[60:63], v[166:169], v[32:47]
	s_waitcnt lgkmcnt(0)
	v_mfma_f32_32x32x16_bf16 v[16:31], v[64:67], v[166:169], v[16:31]
	ds_read_b128 v[60:63], v69
	ds_read_b128 v[64:67], v69 offset:4096
	s_waitcnt lgkmcnt(1)
	v_mfma_f32_32x32x16_bf16 v[32:47], v[60:63], v[170:173], v[32:47]
	s_waitcnt lgkmcnt(0)
	v_mfma_f32_32x32x16_bf16 v[16:31], v[64:67], v[170:173], v[16:31]
	ds_read_b128 v[60:63], v68
	ds_read_b128 v[64:67], v68 offset:4096
	s_waitcnt lgkmcnt(1)
	v_mfma_f32_32x32x16_bf16 v[32:47], v[60:63], v[174:177], v[32:47]
	s_waitcnt lgkmcnt(0)
	v_mfma_f32_32x32x16_bf16 v[16:31], v[64:67], v[174:177], v[16:31]
	s_nop 9
	v_max_f32_e32 v60, v32, v33
	v_max3_f32 v62, v34, v35, v17
	v_max3_f32 v60, v60, v16, v18
	v_max3_f32 v61, v62, v38, v39
	v_max3_f32 v60, v60, v19, v36
	v_max3_f32 v61, v61, v22, v23
	v_max3_f32 v60, v60, v37, v20
	v_max3_f32 v61, v61, v42, v43
	v_max3_f32 v60, v60, v21, v40
	v_max3_f32 v61, v61, v26, v27
	v_max3_f32 v60, v60, v41, v24
	v_max3_f32 v61, v61, v46, v47
	v_max3_f32 v60, v60, v25, v44
	v_max3_f32 v61, v61, v30, v31
	v_max3_f32 v60, v60, v45, v28
	v_max3_f32 v60, v60, v29, v61
	v_mov_b32_e32 v61, v60
	s_nop 1
	v_permlane32_swap_b32_e32 v60, v61
	v_max_f32_e32 v61, v60, v61
	v_exp_f32_e64 v60, -v61
	v_add_f32_e32 v203, 0, v61
	v_xor_b32_e32 v66, 0x80000000, v203
	v_mov_b32_e32 v67, v66
	v_mov_b32_e32 v68, v66
	v_mov_b32_e32 v69, v66
	v_mov_b32_e32 v70, v66
	v_mov_b32_e32 v71, v66
	v_mov_b32_e32 v72, v66
	v_mov_b32_e32 v73, v66
	v_mov_b32_e32 v74, v66
	v_mov_b32_e32 v75, v66
	v_mov_b32_e32 v76, v66
	v_mov_b32_e32 v77, v66
	v_mov_b32_e32 v78, v66
	v_mov_b32_e32 v79, v66
	v_mov_b32_e32 v80, v66
	v_mov_b32_e32 v81, v66
	s_and_saveexec_b64 s[6:7], s[40:41]
	ds_write_b32 v200, v60 offset:128
	s_or_b64 exec, exec, s[6:7]
	v_sub_f32_e32 v32, v32, v61
	v_sub_f32_e32 v33, v33, v61
	v_sub_f32_e32 v82, v16, v61
	v_exp_f32_e32 v16, v32
	v_sub_f32_e32 v34, v34, v61
	v_sub_f32_e32 v83, v17, v61
	v_exp_f32_e32 v17, v33
	v_sub_f32_e32 v35, v35, v61
	v_sub_f32_e32 v84, v18, v61
	v_exp_f32_e32 v18, v34
	v_sub_f32_e32 v36, v36, v61
	v_sub_f32_e32 v85, v19, v61
	v_exp_f32_e32 v19, v35
	v_sub_f32_e32 v37, v37, v61
	v_sub_f32_e32 v86, v20, v61
	v_exp_f32_e32 v20, v36
	v_add_f32_e32 v32, 0, v16
	v_sub_f32_e32 v38, v38, v61
	v_sub_f32_e32 v87, v21, v61
	v_exp_f32_e32 v21, v37
	v_add_f32_e32 v32, v17, v32
	v_sub_f32_e32 v39, v39, v61
	v_sub_f32_e32 v88, v22, v61
	v_exp_f32_e32 v22, v38
	v_add_f32_e32 v32, v18, v32
	v_sub_f32_e32 v40, v40, v61
	v_sub_f32_e32 v89, v23, v61
	v_exp_f32_e32 v23, v39
	v_add_f32_e32 v32, v19, v32
	v_sub_f32_e32 v41, v41, v61
	v_sub_f32_e32 v90, v24, v61
	v_exp_f32_e32 v24, v40
	v_add_f32_e32 v32, v20, v32
	v_sub_f32_e32 v42, v42, v61
	v_sub_f32_e32 v91, v25, v61
	v_exp_f32_e32 v25, v41
	v_add_f32_e32 v32, v21, v32
	v_sub_f32_e32 v43, v43, v61
	v_sub_f32_e32 v92, v26, v61
	v_exp_f32_e32 v26, v42
	v_add_f32_e32 v32, v22, v32
	v_sub_f32_e32 v44, v44, v61
	v_sub_f32_e32 v93, v27, v61
	v_exp_f32_e32 v27, v43
	v_add_f32_e32 v32, v23, v32
	v_sub_f32_e32 v45, v45, v61
	v_sub_f32_e32 v94, v28, v61
	v_exp_f32_e32 v28, v44
	v_add_f32_e32 v32, v24, v32
	s_lshr_b32 s69, s74, 5
	v_sub_f32_e32 v46, v46, v61
	v_sub_f32_e32 v95, v29, v61
	v_exp_f32_e32 v29, v45
	v_add_f32_e32 v32, v25, v32
	v_sub_f32_e32 v47, v47, v61
	v_sub_f32_e32 v96, v30, v61
	s_and_b32 s0, s69, 15
	v_exp_f32_e32 v30, v46
	v_add_f32_e32 v32, v26, v32
	s_movk_i32 s1, 0x70
	v_sub_f32_e32 v97, v31, v61
	s_lshl_b32 s0, s0, 23
	v_exp_f32_e32 v31, v47
	v_add_f32_e32 v32, v27, v32
	v_bitop3_b32 v221, v194, v59, s1 bitop3:0x78
	v_bitop3_b32 v209, v52, v59, s1 bitop3:0x78
	v_bitop3_b32 v208, v53, v59, s1 bitop3:0x78
	v_bitop3_b32 v207, v54, v59, s1 bitop3:0x78
	v_readlane_b32 s1, v254, 9
	v_lshlrev_b32_e32 v62, 4, v50
	v_add_f32_e32 v32, v28, v32
	s_add_u32 s36, s1, s36
	v_readlane_b32 s1, v254, 10
	v_lshlrev_b32_e32 v195, 2, v49
	v_lshlrev_b32_e32 v49, 3, v50
	v_and_b32_e32 v62, 0xc0, v62
	v_lshlrev_b32_e32 v50, 1, v50
	v_add_f32_e32 v32, v29, v32
	s_addc_u32 s37, s1, s37
	v_and_or_b32 v62, v49, 24, v62
	v_and_b32_e32 v50, 32, v50
	v_and_b32_e32 v49, 0x100, v49
	v_add_f32_e32 v32, v30, v32
	s_add_u32 s0, s0, s30
	v_or3_b32 v201, v62, v50, v49
	v_mul_f32_e32 v234, 0, v60
	v_add_f32_e32 v186, v31, v32
	v_cvt_pk_bf16_f32 v182, v16, v17
	v_cvt_pk_bf16_f32 v183, v18, v19
	v_cvt_pk_bf16_f32 v184, v20, v21
	v_cvt_pk_bf16_f32 v185, v22, v23
	v_cvt_pk_bf16_f32 v178, v24, v25
	v_cvt_pk_bf16_f32 v179, v26, v27
	v_cvt_pk_bf16_f32 v180, v28, v29
	v_cvt_pk_bf16_f32 v181, v30, v31
	v_bitop3_b32 v229, v194, v48, s53 bitop3:0x78
	v_bitop3_b32 v230, v194, v204, v51 bitop3:0xde
	v_bitop3_b32 v228, v52, v48, s53 bitop3:0x78
	v_bitop3_b32 v231, v52, v204, v51 bitop3:0xde
	v_bitop3_b32 v227, v53, v48, s53 bitop3:0x78
	v_bitop3_b32 v226, v54, v48, s53 bitop3:0x78
	v_bitop3_b32 v225, v55, v48, s53 bitop3:0x78
	v_bitop3_b32 v224, v56, v48, s53 bitop3:0x78
	v_bitop3_b32 v223, v57, v48, s53 bitop3:0x78
	v_bitop3_b32 v222, v58, v48, s53 bitop3:0x78
	s_addc_u32 s1, 0, s31
	v_readlane_b32 s12, v254, 35
	v_mov_b64_e32 v[64:65], v[14:15]
	v_mov_b64_e32 v[48:49], v[14:15]
	v_mov_b64_e32 v[32:33], v[14:15]
	v_readlane_b32 s13, v254, 36
	s_add_u32 s30, s12, s0
	v_mov_b64_e32 v[62:63], v[12:13]
	v_mov_b64_e32 v[60:61], v[10:11]
	v_mov_b64_e32 v[58:59], v[8:9]
	v_mov_b64_e32 v[56:57], v[6:7]
	v_mov_b64_e32 v[54:55], v[4:5]
	v_mov_b64_e32 v[52:53], v[2:3]
	v_mov_b64_e32 v[50:51], v[0:1]
	v_mov_b64_e32 v[46:47], v[12:13]
	v_mov_b64_e32 v[44:45], v[10:11]
	v_mov_b64_e32 v[42:43], v[8:9]
	v_mov_b64_e32 v[40:41], v[6:7]
	v_mov_b64_e32 v[38:39], v[4:5]
	v_mov_b64_e32 v[36:37], v[2:3]
	v_mov_b64_e32 v[34:35], v[0:1]
	v_mov_b64_e32 v[30:31], v[12:13]
	v_mov_b64_e32 v[28:29], v[10:11]
	v_mov_b64_e32 v[26:27], v[8:9]
	v_mov_b64_e32 v[24:25], v[6:7]
	v_mov_b64_e32 v[22:23], v[4:5]
	v_mov_b64_e32 v[20:21], v[2:3]
	v_mov_b64_e32 v[18:19], v[0:1]
	v_mov_b64_e32 v[16:17], v[14:15]
	s_mov_b32 s70, 1
	v_add_u32_e32 v202, 0, v201
	v_permlane32_swap_b32_e32 v182, v184
	v_permlane32_swap_b32_e32 v183, v185
	v_permlane32_swap_b32_e32 v178, v180
	v_permlane32_swap_b32_e32 v179, v181
	s_mov_b32 s77, 2
	v_add_u32_e32 v232, v229, v204
	v_add_u32_e32 v233, v228, v204
	s_addc_u32 s31, s13, s1
	s_mov_b32 s78, 0
	v_mov_b64_e32 v[14:15], v[12:13]
	v_mov_b64_e32 v[12:13], v[10:11]
	v_mov_b64_e32 v[10:11], v[8:9]
	v_mov_b64_e32 v[8:9], v[6:7]
	v_mov_b64_e32 v[6:7], v[4:5]
	v_mov_b64_e32 v[4:5], v[2:3]
	v_mov_b64_e32 v[2:3], v[0:1]
	s_mov_b32 s0, 0
	v_readlane_b32 s14, v254, 37
	v_readlane_b32 s15, v254, 38
.LBB0_241:
	s_waitcnt vmcnt(5) lgkmcnt(0)
	s_barrier
	s_mov_b32 s79, s70
	s_mov_b32 s70, s0
	s_lshl_b32 s13, s79, 14
	s_lshl_b32 s0, s79, 13
	s_lshl_b32 s1, s70, 14
	s_add_i32 s5, s13, 0
	v_add_u32_e32 v1, s5, v230
	v_add_u32_e32 v102, s5, v232
	ds_read_b128 v[98:101], v1 offset:49152
	ds_read_b128 v[236:239], v102 offset:57344
	v_add_u32_e32 v1, s5, v231
	v_add_u32_e32 v102, s5, v233
	ds_read_b128 v[240:243], v1 offset:49152
	ds_read_b128 v[244:247], v102 offset:57344
	s_waitcnt lgkmcnt(3)
	v_mfma_f32_32x32x16_bf16 v[114:129], v[98:101], v[130:133], v[66:81]
	v_add_u32_e32 v1, s5, v204
	v_add_u32_e32 v102, v1, v227
	ds_read_b128 v[248:251], v102 offset:49152
	v_add_u32_e32 v190, s1, v202
	v_add_u32_e32 v191, s0, v206
	v_exp_f32_e32 v192, v82
	ds_read_b128 v[210:213], v102 offset:57344
	s_waitcnt lgkmcnt(4)
	v_mfma_f32_32x32x16_bf16 v[98:113], v[236:239], v[130:133], v[66:81]
	v_add_f32_e32 v82, v192, v186
	v_exp_f32_e32 v193, v83
	s_waitcnt lgkmcnt(3)
	v_mfma_f32_32x32x16_bf16 v[114:129], v[240:243], v[134:137], v[114:129]
	v_add_u32_e32 v83, v1, v226
	ds_read_b128 v[186:189], v83 offset:49152
	v_add_f32_e32 v82, v193, v82
	v_exp_f32_e32 v235, v84
	s_waitcnt lgkmcnt(3)
	v_mfma_f32_32x32x16_bf16 v[98:113], v[244:247], v[134:137], v[98:113]
	ds_read_b128 v[236:239], v83 offset:57344
	v_add_f32_e32 v240, v235, v82
	v_exp_f32_e32 v220, v85
	s_waitcnt lgkmcnt(3)
	v_mfma_f32_32x32x16_bf16 v[114:129], v[248:251], v[138:141], v[114:129]
	v_add_u32_e32 v241, v1, v225
	ds_read_b128 v[82:85], v241 offset:49152
	v_exp_f32_e32 v244, v86
	v_add_f32_e32 v86, v220, v240
	s_waitcnt lgkmcnt(3)
	v_mfma_f32_32x32x16_bf16 v[98:113], v[210:213], v[138:141], v[98:113]
	ds_read_b128 v[240:243], v241 offset:57344
	v_add_f32_e32 v86, v244, v86
	v_exp_f32_e32 v245, v87
	s_waitcnt lgkmcnt(3)
	v_mfma_f32_32x32x16_bf16 v[114:129], v[186:189], v[142:145], v[114:129]
	v_add_u32_e32 v87, v1, v224
	ds_read_b128 v[210:213], v87 offset:49152
	v_add_f32_e32 v86, v245, v86
	v_exp_f32_e32 v246, v88
	s_waitcnt lgkmcnt(3)
	v_mfma_f32_32x32x16_bf16 v[98:113], v[236:239], v[142:145], v[98:113]
	ds_read_b128 v[186:189], v87 offset:57344
	v_add_f32_e32 v248, v246, v86
	v_exp_f32_e32 v247, v89
	s_waitcnt lgkmcnt(3)
	v_mfma_f32_32x32x16_bf16 v[114:129], v[82:85], v[154:157], v[114:129]
	v_add_u32_e32 v236, v1, v223
	ds_read_b128 v[86:89], v236 offset:49152
	v_add_f32_e32 v82, v247, v248
	v_exp_f32_e32 v249, v90
	s_waitcnt lgkmcnt(3)
	v_mfma_f32_32x32x16_bf16 v[98:113], v[240:243], v[154:157], v[98:113]
	ds_read_b128 v[236:239], v236 offset:57344
	v_add_f32_e32 v84, v249, v82
	v_exp_f32_e32 v248, v91
	v_cvt_pk_bf16_f32 v82, v192, v193
	v_cvt_pk_bf16_f32 v83, v235, v220
	s_waitcnt lgkmcnt(3)
	v_mfma_f32_32x32x16_bf16 v[114:129], v[210:213], v[150:153], v[114:129]
	v_add_u32_e32 v1, v1, v222
	ds_read_b128 v[240:243], v1 offset:49152
	v_add_f32_e32 v90, v248, v84
	v_exp_f32_e32 v192, v92
	v_cvt_pk_bf16_f32 v84, v244, v245
	v_cvt_pk_bf16_f32 v85, v246, v247
	s_waitcnt lgkmcnt(3)
; #define MX3(a, b, c) __builtin_fmaxf(__builtin_fmaxf((a), (b)), (c))
; #define MX3(a, b, c) __builtin_fmaxf(__builtin_fmaxf((a), (b)), (c))
; __device__ __forceinline__ float rowmax32(const f32x16& p0, const f32x16& p1) {
;   float a = MX3(p0[0], p0[1], p1[0]), b = MX3(p0[2], p0[3], p1[1]); a = MX3(a, p1[2], p1[3]);
; #pragma unroll
;   for (int r = 4; r < 16; r += 4) { a = MX3(a, p0[r], p0[r + 1]); b = MX3(b, p0[r + 2], p0[r + 3]); a = MX3(a, p1[r], p1[r + 1]); b = MX3(b, p1[r + 2], p1[r + 3]); }
;   float m = __builtin_fmaxf(a, b);
;   auto rr = __builtin_amdgcn_permlane32_swap(__float_as_uint(m), __float_as_uint(m), false, false);
;   return __builtin_fmaxf(__uint_as_float(rr[0]), __uint_as_float(rr[1]));
; }
	v_mfma_f32_32x32x16_bf16 v[98:113], v[186:189], v[150:153], v[98:113]
	ds_read_b128 v[210:213], v1 offset:57344
	v_exp_f32_e32 v1, v93
	v_add_f32_e32 v193, v192, v90
	v_permlane32_swap_b32_e32 v82, v84
	v_permlane32_swap_b32_e32 v83, v85
	s_waitcnt lgkmcnt(3)
	v_mfma_f32_32x32x16_bf16 v[114:129], v[86:89], v[146:149], v[114:129]
	v_add_u32_e32 v186, v191, v221
	ds_read_b128 v[90:93], v186
	v_exp_f32_e32 v220, v94
	v_add_f32_e32 v94, v1, v193
	s_waitcnt lgkmcnt(3)
	v_mfma_f32_32x32x16_bf16 v[98:113], v[236:239], v[146:149], v[98:113]
	ds_read_b128 v[86:89], v186 offset:4096
	v_add_f32_e32 v94, v220, v94
	v_exp_f32_e32 v193, v95
	s_waitcnt lgkmcnt(3)
	v_mfma_f32_32x32x16_bf16 v[114:129], v[240:243], v[158:161], v[114:129]
	v_add_u32_e32 v95, v191, v209
	ds_read_b128 v[186:189], v95
	v_add_f32_e32 v94, v193, v94
	v_exp_f32_e32 v235, v96
	s_waitcnt lgkmcnt(3)
	v_mfma_f32_32x32x16_bf16 v[98:113], v[210:213], v[158:161], v[98:113]
	ds_read_b128 v[236:239], v95 offset:4096
	v_add_f32_e32 v241, v235, v94
	v_exp_f32_e32 v240, v97
	s_waitcnt lgkmcnt(3)
	v_mfma_f32_32x32x16_bf16 v[114:129], v[90:93], v[162:165], v[114:129]
	v_add_u32_e32 v210, v191, v208
	ds_read_b128 v[94:97], v210
	v_add_f32_e32 v241, v240, v241
	s_waitcnt lgkmcnt(3)
	v_mfma_f32_32x32x16_bf16 v[98:113], v[86:89], v[162:165], v[98:113]
	ds_read_b128 v[90:93], v210 offset:4096
	v_cvt_pk_bf16_f32 v86, v249, v248
	v_cvt_pk_bf16_f32 v87, v192, v1
	s_waitcnt lgkmcnt(3)
	v_mfma_f32_32x32x16_bf16 v[114:129], v[186:189], v[166:169], v[114:129]
	v_add_u32_e32 v1, v191, v207
	ds_read_b128 v[210:213], v1
	v_cvt_pk_bf16_f32 v88, v220, v193
	v_cvt_pk_bf16_f32 v89, v235, v240
	s_waitcnt lgkmcnt(3)
	v_mfma_f32_32x32x16_bf16 v[98:113], v[236:239], v[166:169], v[98:113]
	ds_read_b128 v[186:189], v1 offset:4096
	v_permlane32_swap_b32_e32 v86, v88
	v_permlane32_swap_b32_e32 v87, v89
	s_waitcnt lgkmcnt(3)
	v_mfma_f32_32x32x16_bf16 v[114:129], v[94:97], v[170:173], v[114:129]
	v_mov_b32_e32 v1, v241
	s_nop 1
	v_permlane32_swap_b32_e32 v241, v1
	v_add_f32_e32 v1, v241, v1
	v_add_f32_e32 v1, v234, v1
	s_waitcnt lgkmcnt(2)
	v_mfma_f32_32x32x16_bf16 v[98:113], v[90:93], v[170:173], v[98:113]
	ds_read_b64_tr_b16 v[94:95], v190
	ds_read_b64_tr_b16 v[96:97], v190 offset:2048
	s_waitcnt lgkmcnt(3)
	v_mfma_f32_32x32x16_bf16 v[114:129], v[210:213], v[174:177], v[114:129]
	ds_read_b64_tr_b16 v[90:91], v190 offset:512
	ds_read_b64_tr_b16 v[92:93], v190 offset:2560
	s_waitcnt lgkmcnt(4)
	v_mfma_f32_32x32x16_bf16 v[98:113], v[186:189], v[174:177], v[98:113]
	ds_read_b64_tr_b16 v[210:211], v190 offset:1024
	ds_read_b64_tr_b16 v[212:213], v190 offset:3072
	s_add_u32 s18, s30, s46
	s_addc_u32 s19, s31, s47
	s_add_u32 s14, s18, 0x15000000
	s_addc_u32 s15, s19, 0
	s_waitcnt lgkmcnt(4)
	v_mfma_f32_32x32x16_bf16 v[50:65], v[182:185], v[94:97], v[50:65]
	s_add_u32 s6, s18, 0x15018000
	s_addc_u32 s7, s19, 0
	s_add_i32 s5, s1, s76
	s_add_u32 s8, s18, 0x15010100
	ds_read_b64_tr_b16 v[234:235], v190 offset:1536
	ds_read_b64_tr_b16 v[236:237], v190 offset:3584
	s_addc_u32 s9, s19, 0
	s_lshl_b32 s20, s77, 14
	s_add_i32 s12, s20, s73
	s_mov_b32 m0, s12
	s_nop 0
	global_load_lds_dwordx4 v199, s[8:9]
	s_waitcnt lgkmcnt(4)
	v_mfma_f32_32x32x16_bf16 v[34:49], v[182:185], v[90:93], v[34:49]
	ds_read_b64_tr_b16 v[94:95], v190 offset:4096
	ds_read_b64_tr_b16 v[96:97], v190 offset:6144
	s_add_u32 s8, s18, 0x15014100
	s_addc_u32 s9, s19, 0
	s_addk_i32 s12, 0x2000
	s_mov_b32 m0, s12
	s_nop 0
	global_load_lds_dwordx4 v199, s[8:9]
	s_waitcnt lgkmcnt(4)
	v_mfma_f32_32x32x16_bf16 v[18:33], v[182:185], v[210:213], v[18:33]
	ds_read_b64_tr_b16 v[186:187], v190 offset:4608
	ds_read_b64_tr_b16 v[188:189], v190 offset:6656
	s_mov_b32 m0, s5
	s_nop 0
	global_load_lds_dwordx4 v197, s[6:7]
	s_waitcnt lgkmcnt(4)
	v_mfma_f32_32x32x16_bf16 v[2:17], v[182:185], v[234:237], v[2:17]
	ds_read_b64_tr_b16 v[90:91], v190 offset:5120
	ds_read_b64_tr_b16 v[92:93], v190 offset:7168
	s_add_u32 s6, s18, 0x1501a000
	s_addc_u32 s7, s19, 0
	s_addk_i32 s5, 0x1000
	s_mov_b32 m0, s5
	s_nop 0
	global_load_lds_dwordx4 v197, s[6:7]
	v_max_f32_e32 v182, v114, v115
	v_max3_f32 v183, v116, v117, v99
	v_max3_f32 v182, v182, v98, v100
	v_max3_f32 v182, v182, v101, v118
	v_max3_f32 v183, v183, v120, v121
	v_max3_f32 v182, v182, v119, v102
	v_max3_f32 v183, v183, v104, v105
	v_max3_f32 v182, v182, v103, v122
	v_max3_f32 v183, v183, v124, v125
	v_max3_f32 v182, v182, v123, v106
	v_max3_f32 v183, v183, v108, v109
	v_max3_f32 v182, v182, v107, v126
	v_max3_f32 v183, v183, v128, v129
	v_max3_f32 v182, v182, v127, v110
	v_max3_f32 v183, v183, v112, v113
	v_max3_f32 v182, v182, v111, v183
	v_mov_b32_e32 v183, v182
	s_nop 1
	v_permlane32_swap_b32_e32 v182, v183
	v_max_f32_e32 v182, v182, v183
	v_cmp_lt_f32_e32 vcc, s92, v182
	s_cmp_lg_u64 vcc, 0
	s_cselect_b64 s[6:7], -1, 0
	s_cbranch_vccnz .LBB0_255

; #define MX3(a, b, c) __builtin_fmaxf(__builtin_fmaxf((a), (b)), (c))
; #define MX3(a, b, c) __builtin_fmaxf(__builtin_fmaxf((a), (b)), (c))
; __device__ __forceinline__ float rowmax32(const f32x16& p0, const f32x16& p1) {
;   float a = MX3(p0[0], p0[1], p1[0]), b = MX3(p0[2], p0[3], p1[1]); a = MX3(a, p1[2], p1[3]);
; #pragma unroll
;   for (int r = 4; r < 16; r += 4) { a = MX3(a, p0[r], p0[r + 1]); b = MX3(b, p0[r + 2], p0[r + 3]); a = MX3(a, p1[r], p1[r + 1]); b = MX3(b, p1[r + 2], p1[r + 3]); }
;   float m = __builtin_fmaxf(a, b);
;   auto rr = __builtin_amdgcn_permlane32_swap(__float_as_uint(m), __float_as_uint(m), false, false);
;   return __builtin_fmaxf(__uint_as_float(rr[0]), __uint_as_float(rr[1]));
; }
.LBB0_248:
	s_waitcnt lgkmcnt(6)
	v_mfma_f32_32x32x16_bf16 v[2:17], v[182:185], v[190:193], v[2:17]
	v_max_f32_e32 v1, v114, v115
	v_max3_f32 v182, v116, v117, v83
	v_max3_f32 v1, v1, v82, v84
	v_max3_f32 v1, v1, v85, v118
	v_max3_f32 v182, v182, v120, v121
	v_max3_f32 v1, v1, v119, v86
	v_max3_f32 v182, v182, v88, v89
	v_max3_f32 v1, v1, v87, v122
	v_max3_f32 v182, v182, v124, v125
	v_max3_f32 v1, v1, v123, v90
	v_max3_f32 v182, v182, v92, v93
	v_max3_f32 v1, v1, v91, v126
	v_max3_f32 v182, v182, v128, v129
	v_max3_f32 v1, v1, v127, v94
	v_max3_f32 v182, v182, v96, v97
	v_max3_f32 v1, v1, v95, v182
	v_mov_b32_e32 v182, v1
	s_nop 1
	v_permlane32_swap_b32_e32 v1, v182
	v_max_f32_e32 v1, v1, v182
	v_cmp_lt_f32_e32 vcc, s92, v1
	s_cmp_lg_u64 vcc, 0
	s_cselect_b64 s[6:7], -1, 0
	s_cbranch_vccnz .LBB0_258

; __device__ __forceinline__ void mla_unit(char* lds, const bf16_t* __restrict__ Qp, const bf16_t* __restrict__ Knp, const bf16_t* __restrict__ Vp, ...
;     ...
;   int j = 0;
;   for (; j + 2 < NT; j += 2) { STEP(pA0, pA1, pB0, pB1, j); STEP(pB0, pB1, pA0, pA1, j + 1); }
;   STEP(pA0, pA1, pB0, pB1, j);
.LBB0_261:
	s_waitcnt vmcnt(2) lgkmcnt(0)
	s_barrier
	s_add_i32 s0, 0, 0x10000
	v_add_u32_e32 v1, s0, v204
	v_add_u32_e32 v98, v1, v229
	ds_read_b128 v[114:117], v98
	ds_read_b128 v[118:121], v98 offset:8192
	v_add_u32_e32 v98, v1, v228
	ds_read_b128 v[122:125], v98
	ds_read_b128 v[126:129], v98 offset:8192
	s_waitcnt lgkmcnt(3)
	v_mfma_f32_32x32x16_bf16 v[98:113], v[114:117], v[130:133], v[66:81]
	v_add_u32_e32 v192, v1, v227
	ds_read_b128 v[188:191], v192
	s_add_i32 s0, 0, 0x1a000
	v_add_u32_e32 v187, s0, v205
	v_exp_f32_e32 v193, v82
	s_waitcnt lgkmcnt(3)
	v_mfma_f32_32x32x16_bf16 v[66:81], v[118:121], v[130:133], v[66:81]
	ds_read_b128 v[114:117], v192 offset:8192
	v_add_f32_e32 v82, v193, v186
	v_exp_f32_e32 v192, v83
	s_waitcnt lgkmcnt(3)
	v_mfma_f32_32x32x16_bf16 v[98:113], v[122:125], v[134:137], v[98:113]
	v_add_u32_e32 v83, v1, v226
	ds_read_b128 v[118:121], v83
	v_add_f32_e32 v82, v192, v82
	v_exp_f32_e32 v186, v84
	s_waitcnt lgkmcnt(3)
	v_mfma_f32_32x32x16_bf16 v[66:81], v[126:129], v[134:137], v[66:81]
	ds_read_b128 v[122:125], v83 offset:8192
	v_add_f32_e32 v130, v186, v82
	v_exp_f32_e32 v204, v85
	s_waitcnt lgkmcnt(3)
	v_mfma_f32_32x32x16_bf16 v[98:113], v[188:191], v[138:141], v[98:113]
	v_add_u32_e32 v126, v1, v225
	ds_read_b128 v[82:85], v126
	v_exp_f32_e32 v134, v86
	v_add_f32_e32 v86, v204, v130
	s_waitcnt lgkmcnt(3)
	v_mfma_f32_32x32x16_bf16 v[66:81], v[114:117], v[138:141], v[66:81]
	ds_read_b128 v[126:129], v126 offset:8192
	v_add_f32_e32 v86, v134, v86
	v_exp_f32_e32 v135, v87
	s_waitcnt lgkmcnt(3)
	v_mfma_f32_32x32x16_bf16 v[98:113], v[118:121], v[142:145], v[98:113]
	v_add_u32_e32 v87, v1, v224
	ds_read_b128 v[130:133], v87
	v_exp_f32_e32 v117, v88
	v_add_f32_e32 v86, v135, v86
	s_waitcnt lgkmcnt(3)
	v_mfma_f32_32x32x16_bf16 v[66:81], v[122:125], v[142:145], v[66:81]
	ds_read_b128 v[118:121], v87 offset:8192
	v_add_f32_e32 v114, v117, v86
	v_exp_f32_e32 v136, v89
	s_waitcnt lgkmcnt(3)
	v_mfma_f32_32x32x16_bf16 v[98:113], v[82:85], v[154:157], v[98:113]
	v_add_u32_e32 v115, v1, v223
	ds_read_b128 v[86:89], v115
	v_exp_f32_e32 v137, v90
	v_add_f32_e32 v90, v136, v114
	s_waitcnt lgkmcnt(3)
	v_mfma_f32_32x32x16_bf16 v[66:81], v[126:129], v[154:157], v[66:81]
	ds_read_b128 v[82:85], v115 offset:8192
	v_add_f32_e32 v90, v137, v90
	v_exp_f32_e32 v138, v91
	v_cvt_pk_bf16_f32 v114, v193, v192
	v_cvt_pk_bf16_f32 v115, v186, v204
	s_waitcnt lgkmcnt(3)
	v_mfma_f32_32x32x16_bf16 v[98:113], v[130:133], v[150:153], v[98:113]
	v_add_u32_e32 v1, v1, v222
	ds_read_b128 v[122:125], v1
	v_exp_f32_e32 v130, v92
	v_add_f32_e32 v90, v138, v90
	v_cvt_pk_bf16_f32 v116, v134, v135
	v_cvt_pk_bf16_f32 v117, v117, v136
	s_waitcnt lgkmcnt(3)
	v_mfma_f32_32x32x16_bf16 v[66:81], v[118:121], v[150:153], v[66:81]
	ds_read_b128 v[126:129], v1 offset:8192
	v_exp_f32_e32 v1, v93
	v_add_f32_e32 v131, v130, v90
	v_permlane32_swap_b32_e32 v114, v116
	v_permlane32_swap_b32_e32 v115, v117
	s_waitcnt lgkmcnt(3)
	v_mfma_f32_32x32x16_bf16 v[98:113], v[86:89], v[146:149], v[98:113]
	v_add_u32_e32 v118, v187, v221
	ds_read_b128 v[90:93], v118
	v_exp_f32_e32 v120, v94
	v_add_f32_e32 v94, v1, v131
	s_waitcnt lgkmcnt(3)
	v_mfma_f32_32x32x16_bf16 v[66:81], v[82:85], v[146:149], v[66:81]
	ds_read_b128 v[86:89], v118 offset:4096
	v_exp_f32_e32 v121, v95
	v_add_f32_e32 v94, v120, v94
	s_waitcnt lgkmcnt(3)
	v_mfma_f32_32x32x16_bf16 v[98:113], v[122:125], v[158:161], v[98:113]
	v_add_u32_e32 v95, v187, v209
	ds_read_b128 v[82:85], v95
	v_exp_f32_e32 v131, v96
	v_add_f32_e32 v94, v121, v94
	s_waitcnt lgkmcnt(3)
	v_mfma_f32_32x32x16_bf16 v[66:81], v[126:129], v[158:161], v[66:81]
	ds_read_b128 v[122:125], v95 offset:4096
	v_exp_f32_e32 v132, v97
	v_add_f32_e32 v118, v131, v94
	s_waitcnt lgkmcnt(3)
	v_mfma_f32_32x32x16_bf16 v[98:113], v[90:93], v[162:165], v[98:113]
	v_add_u32_e32 v119, v187, v208
	ds_read_b128 v[94:97], v119
	v_add_f32_e32 v126, v132, v118
	s_waitcnt lgkmcnt(3)
	v_mfma_f32_32x32x16_bf16 v[66:81], v[86:89], v[162:165], v[66:81]
	ds_read_b128 v[90:93], v119 offset:4096
	v_cvt_pk_bf16_f32 v118, v137, v138
	v_cvt_pk_bf16_f32 v119, v130, v1
	s_waitcnt lgkmcnt(3)
	v_mfma_f32_32x32x16_bf16 v[98:113], v[82:85], v[166:169], v[98:113]
	v_add_u32_e32 v1, v187, v207
	ds_read_b128 v[86:89], v1
	v_cvt_pk_bf16_f32 v120, v120, v121
	v_cvt_pk_bf16_f32 v121, v131, v132
	s_waitcnt lgkmcnt(3)
	v_mfma_f32_32x32x16_bf16 v[66:81], v[122:125], v[166:169], v[66:81]
	ds_read_b128 v[82:85], v1 offset:4096
	v_permlane32_swap_b32_e32 v118, v120
	v_permlane32_swap_b32_e32 v119, v121
	s_waitcnt lgkmcnt(3)
	v_mfma_f32_32x32x16_bf16 v[98:113], v[94:97], v[170:173], v[98:113]
	v_mov_b32_e32 v1, v126
	s_nop 1
	v_permlane32_swap_b32_e32 v126, v1
	v_add_f32_e32 v1, v126, v1
	v_add_f32_e32 v1, v234, v1
	s_waitcnt lgkmcnt(2)
	v_mfma_f32_32x32x16_bf16 v[66:81], v[90:93], v[170:173], v[66:81]
	ds_read_b64_tr_b16 v[94:95], v202
	ds_read_b64_tr_b16 v[96:97], v202 offset:2048
	s_waitcnt lgkmcnt(3)
	v_mfma_f32_32x32x16_bf16 v[98:113], v[86:89], v[174:177], v[98:113]
	ds_read_b64_tr_b16 v[90:91], v202 offset:512
	ds_read_b64_tr_b16 v[92:93], v202 offset:2560
	s_waitcnt lgkmcnt(4)
	v_mfma_f32_32x32x16_bf16 v[66:81], v[82:85], v[174:177], v[66:81]
	ds_read_b64_tr_b16 v[86:87], v202 offset:1024
	ds_read_b64_tr_b16 v[88:89], v202 offset:3072
	s_waitcnt lgkmcnt(4)
	v_mfma_f32_32x32x16_bf16 v[50:65], v[182:185], v[94:97], v[50:65]
	ds_read_b64_tr_b16 v[82:83], v202 offset:1536
	ds_read_b64_tr_b16 v[84:85], v202 offset:3584
	s_waitcnt lgkmcnt(4)
	v_mfma_f32_32x32x16_bf16 v[34:49], v[182:185], v[90:93], v[34:49]
	ds_read_b64_tr_b16 v[130:131], v202 offset:4096
	ds_read_b64_tr_b16 v[132:133], v202 offset:6144
	s_waitcnt lgkmcnt(4)
	v_mfma_f32_32x32x16_bf16 v[18:33], v[182:185], v[86:89], v[18:33]
	ds_read_b64_tr_b16 v[126:127], v202 offset:4608
	ds_read_b64_tr_b16 v[128:129], v202 offset:6656
	s_waitcnt lgkmcnt(4)
	v_mfma_f32_32x32x16_bf16 v[2:17], v[182:185], v[82:85], v[2:17]
	ds_read_b64_tr_b16 v[122:123], v202 offset:5120
	ds_read_b64_tr_b16 v[124:125], v202 offset:7168
	v_max_f32_e32 v82, v98, v99
	v_max3_f32 v83, v100, v101, v67
	v_max3_f32 v82, v82, v66, v68
	v_max3_f32 v82, v82, v69, v102
	v_max3_f32 v83, v83, v104, v105
	v_max3_f32 v82, v82, v103, v70
	v_max3_f32 v83, v83, v72, v73
	v_max3_f32 v82, v82, v71, v106
	v_max3_f32 v83, v83, v108, v109
	v_max3_f32 v82, v82, v107, v74
	v_max3_f32 v83, v83, v76, v77
	v_max3_f32 v82, v82, v75, v110
	v_max3_f32 v83, v83, v112, v113
	v_max3_f32 v82, v82, v111, v78
	v_max3_f32 v83, v83, v80, v81
	v_max3_f32 v82, v82, v79, v83
	v_mov_b32_e32 v83, v82
	s_nop 1
	v_permlane32_swap_b32_e32 v82, v83
	v_max_f32_e32 v82, v82, v83
	v_cmp_lt_f32_e32 vcc, s92, v82
	s_cmp_lg_u64 vcc, 0
	s_cselect_b64 s[6:7], -1, 0
	s_cbranch_vccnz .LBB0_268

; #define EXP16(P) do { _Pragma("unroll") for (int r = 0; r < 16; ++r) P[r] = __builtin_amdgcn_exp2f(P[r]); } while (0)
; #define WAIT_BAR4() asm volatile("s_waitcnt vmcnt(4) lgkmcnt(0)\n\ts_barrier" ::: "memory")
; #define EXP16(P) do { _Pragma("unroll") for (int r = 0; r < 16; ++r) P[r] = __builtin_amdgcn_exp2f(P[r]); } while (0)
; __device__ __forceinline__ void na_unit3(char* lds, const bf16_t* __restrict__ Qp, const bf16_t* __restrict__ Knp, const bf16_t* __restrict__ Vp, ...
;     ...
;   int s0 = 0, s1 = 1, s3 = 3;
;   WAIT_BAR4();
;   if (t_lo == 0) { QK_PLAIN(pA0, pA1, 0); MASKB(pA0, pA1, 0, true); NEWMAX(pA0, pA1, true); EXP16(pA0); HALF0(pA0); }
.LBB0_284:
	s_or_b64 exec, exec, s[6:7]
	s_bfe_u32 s9, s10, 0x10006
	v_lshl_or_b32 v226, s9, 5, v221
	s_and_b32 s5, s10, 0x3fffffc0
	s_ashr_i32 s8, s10, 7
	v_sub_u32_e64 v1, v226, 8 clamp
	v_mov_b32_e32 v14, v0
	v_mov_b32_e32 v15, v0
	v_and_b32_e32 v205, 63, v2
	s_lshl_b32 s5, s5, 2
	s_add_i32 s94, s8, s1
	v_min_u32_e32 v16, 48, v1
	v_mov_b32_e32 v1, v0
	v_mov_b32_e32 v2, v0
	v_mov_b32_e32 v3, v0
	v_mov_b32_e32 v4, v0
	v_mov_b32_e32 v5, v0
	v_mov_b32_e32 v6, v0
	v_mov_b32_e32 v7, v0
	v_mov_b32_e32 v8, v0
	v_mov_b32_e32 v9, v0
	v_mov_b32_e32 v10, v0
	v_mov_b32_e32 v11, v0
	v_mov_b32_e32 v12, v0
	v_mov_b32_e32 v13, v0
	v_mov_b64_e32 v[94:95], v[14:15]
	s_add_i32 s26, s5, 0
	s_max_i32 s5, s94, 4
	v_mov_b64_e32 v[92:93], v[12:13]
	v_mov_b64_e32 v[90:91], v[10:11]
	v_mov_b64_e32 v[88:89], v[8:9]
	v_mov_b64_e32 v[86:87], v[6:7]
	v_mov_b64_e32 v[84:85], v[4:5]
	v_mov_b64_e32 v[82:83], v[2:3]
	v_mov_b64_e32 v[80:81], v[0:1]
	s_add_i32 s5, s5, -4
	s_waitcnt vmcnt(4) lgkmcnt(0)
	s_barrier
	s_add_i32 s26, s26, 0x20000
	s_lshl_b32 s27, s9, 4
	s_min_u32 s10, s5, 0x78
	s_cmp_eq_u32 s10, s85
	v_and_b32_e32 v1, 0xf0, v18
	v_sub_u32_e32 v227, v226, v16
	v_cmp_gt_u32_e32 vcc, 32, v205
	s_cbranch_scc0 .LBB0_288
	v_add_u32_e32 v2, s27, v221
	s_add_i32 s5, 0, 0x10000
	v_bitop3_b32 v3, v204, v18, s53 bitop3:0x78
	v_lshl_add_u32 v19, v2, 8, s5
	v_add_u32_e32 v2, v19, v3
	v_add_u32_e32 v4, 0x2000, v19
	v_add_u32_e32 v3, v4, v3
	ds_read_b128 v[20:23], v2
	ds_read_b128 v[24:27], v3
	v_bitop3_b32 v2, v204, v1, 32 bitop3:0x36
	v_add_u32_e32 v3, v19, v2
	v_add_u32_e32 v2, v4, v2
	ds_read_b128 v[28:31], v3
	ds_read_b128 v[32:35], v2
	v_or_b32_e32 v2, 64, v204
	v_xad_u32 v40, v2, v1, v19
	s_waitcnt lgkmcnt(3)
	v_mfma_f32_32x32x16_bf16 v[2:17], v[20:23], v[160:163], v[80:95]
	ds_read_b128 v[36:39], v40
	s_waitcnt lgkmcnt(3)
	v_mfma_f32_32x32x16_bf16 v[80:95], v[24:27], v[160:163], v[80:95]
	ds_read_b128 v[20:23], v40 offset:8192
	s_waitcnt lgkmcnt(3)
	v_mfma_f32_32x32x16_bf16 v[2:17], v[28:31], v[164:167], v[2:17]
	v_or_b32_e32 v24, 0x60, v204
	v_xad_u32 v40, v24, v1, v19
	ds_read_b128 v[24:27], v40
	s_waitcnt lgkmcnt(3)
	v_mfma_f32_32x32x16_bf16 v[80:95], v[32:35], v[164:167], v[80:95]
	ds_read_b128 v[28:31], v40 offset:8192
	s_waitcnt lgkmcnt(3)
	v_mfma_f32_32x32x16_bf16 v[2:17], v[36:39], v[168:171], v[2:17]
	v_or_b32_e32 v32, 0x80, v204
	v_xad_u32 v40, v32, v1, v19
	ds_read_b128 v[32:35], v40
	s_waitcnt lgkmcnt(3)
	v_mfma_f32_32x32x16_bf16 v[80:95], v[20:23], v[168:171], v[80:95]
	ds_read_b128 v[36:39], v40 offset:8192
	s_waitcnt lgkmcnt(3)
	v_mfma_f32_32x32x16_bf16 v[2:17], v[24:27], v[172:175], v[2:17]
	v_or_b32_e32 v20, 0xa0, v204
	v_xad_u32 v40, v20, v1, v19
	ds_read_b128 v[20:23], v40
	s_waitcnt lgkmcnt(3)
	v_mfma_f32_32x32x16_bf16 v[80:95], v[28:31], v[172:175], v[80:95]
	ds_read_b128 v[24:27], v40 offset:8192
	s_waitcnt lgkmcnt(3)
	v_mfma_f32_32x32x16_bf16 v[2:17], v[32:35], v[176:179], v[2:17]
	v_or_b32_e32 v28, 0xc0, v204
	v_xad_u32 v40, v28, v1, v19
	ds_read_b128 v[28:31], v40
	s_waitcnt lgkmcnt(3)
	v_mfma_f32_32x32x16_bf16 v[80:95], v[36:39], v[176:179], v[80:95]
	ds_read_b128 v[32:35], v40 offset:8192
	s_waitcnt lgkmcnt(3)
	v_mfma_f32_32x32x16_bf16 v[2:17], v[20:23], v[180:183], v[2:17]
	v_or_b32_e32 v36, 0xe0, v204
	v_xad_u32 v19, v36, v1, v19
	ds_read_b128 v[36:39], v19
	s_waitcnt lgkmcnt(3)
	v_mfma_f32_32x32x16_bf16 v[80:95], v[24:27], v[180:183], v[80:95]
	ds_read_b128 v[20:23], v19 offset:8192
	s_waitcnt lgkmcnt(3)
	v_mfma_f32_32x32x16_bf16 v[2:17], v[28:31], v[184:187], v[2:17]
	s_waitcnt lgkmcnt(2)
	v_mfma_f32_32x32x16_bf16 v[80:95], v[32:35], v[184:187], v[80:95]
	s_waitcnt lgkmcnt(1)
	v_mfma_f32_32x32x16_bf16 v[2:17], v[36:39], v[188:191], v[2:17]
	s_waitcnt lgkmcnt(0)
	v_mfma_f32_32x32x16_bf16 v[80:95], v[20:23], v[188:191], v[80:95]
	s_sub_i32 s5, s85, s94
	s_mulk_i32 s5, 0x7c
	v_lshl_or_b32 v19, v222, 2, s27
	s_add_i32 s5, s5, 0
	v_sub_u32_e32 v19, v19, v226
	s_add_i32 s5, s5, 0x20c00
	s_nop 0
	v_lshl_add_u32 v36, v19, 2, s5
	v_add_u32_e32 v32, 0x400, v36
	v_add_u32_e32 v34, 0x408, v36
	ds_read2_b32 v[20:21], v36 offset0:232 offset1:233
	ds_read2_b32 v[22:23], v36 offset0:234 offset1:235
	ds_read2_b32 v[24:25], v36 offset0:240 offset1:241
	ds_read2_b32 v[26:27], v36 offset0:242 offset1:243
	ds_read2_b32 v[28:29], v36 offset0:248 offset1:249
	ds_read2_b32 v[30:31], v36 offset0:250 offset1:251
	ds_read2_b32 v[32:33], v32 offset1:1
	ds_read2_b32 v[34:35], v34 offset1:1
	v_add_u32_e32 v37, 0x420, v36
	v_add_u32_e32 v38, 0x428, v36
	v_add_u32_e32 v40, 0x440, v36
	v_add_u32_e32 v42, 0x448, v36
	v_add_u32_e32 v44, v19, v227
	ds_read2_b32 v[36:37], v37 offset1:1
	ds_read2_b32 v[38:39], v38 offset1:1
	ds_read2_b32 v[40:41], v40 offset1:1
	ds_read2_b32 v[42:43], v42 offset1:1
	s_waitcnt lgkmcnt(11)
	v_cmp_gt_u32_e64 s[40:41], 16, v44
	v_add_f32_e32 v2, v2, v20
	s_waitcnt lgkmcnt(10)
	s_waitcnt lgkmcnt(9)
	v_cndmask_b32_e64 v19, v214, v2, s[40:41]
	v_and_b32_e32 v2, -16, v44
	s_waitcnt lgkmcnt(8)
	s_waitcnt lgkmcnt(7)
	s_waitcnt lgkmcnt(6)
	s_waitcnt lgkmcnt(5)
	s_waitcnt lgkmcnt(4)
	s_waitcnt lgkmcnt(3)
	v_cmp_eq_u32_e64 s[40:41], s96, v2
	v_add_f32_e32 v20, v80, v36
	v_add_u32_e32 v2, 1, v44
	v_cndmask_b32_e64 v20, v214, v20, s[40:41]
	v_add_f32_e32 v3, v3, v21
	v_cmp_gt_u32_e64 s[40:41], 16, v2
	v_add_u32_e32 v2, 2, v44
	s_waitcnt lgkmcnt(2)
	s_waitcnt lgkmcnt(1)
	v_cndmask_b32_e64 v21, v214, v3, s[40:41]
	v_add_f32_e32 v3, v4, v22
	v_cmp_gt_u32_e64 s[40:41], 16, v2
	v_add_u32_e32 v2, 3, v44
	s_waitcnt lgkmcnt(0)
	v_mov_b32_e32 v4, v37
	v_cndmask_b32_e64 v22, v214, v3, s[40:41]
	v_add_f32_e32 v3, v5, v23
	v_cmp_gt_u32_e64 s[40:41], 16, v2
	v_add_u32_e32 v2, 8, v44
	v_mov_b32_e32 v5, v38
	v_cndmask_b32_e64 v23, v214, v3, s[40:41]
	v_add_f32_e32 v3, v6, v24
	v_cmp_gt_u32_e64 s[40:41], 16, v2
	v_add_u32_e32 v2, 9, v44
	v_max_f32_e32 v6, v19, v21
	v_cndmask_b32_e64 v24, v214, v3, s[40:41]
	v_add_f32_e32 v3, v7, v25
	v_cmp_gt_u32_e64 s[40:41], 16, v2
	v_add_u32_e32 v2, 10, v44
	s_nop 0
	v_cndmask_b32_e64 v7, v214, v3, s[40:41]
	v_add_f32_e32 v3, v8, v26
	v_cmp_gt_u32_e64 s[40:41], 16, v2
	v_add_u32_e32 v2, 11, v44
	v_add_u32_e32 v8, 34, v44
	v_cndmask_b32_e64 v25, v214, v3, s[40:41]
	v_add_f32_e32 v3, v9, v27
	v_cmp_gt_u32_e64 s[40:41], 16, v2
	v_add_u32_e32 v2, 43, v44
	v_add_u32_e32 v9, 33, v44
	v_cndmask_b32_e64 v26, v214, v3, s[40:41]
	v_add_f32_e32 v3, v87, v43
	v_cmp_gt_u32_e64 s[40:41], 16, v2
	v_add_f32_e32 v2, v10, v28
	v_add_u32_e32 v28, 40, v44
	v_cndmask_b32_e64 v27, v214, v3, s[40:41]
	v_cmp_lt_u32_e64 s[40:41], s97, v44
	v_add_f32_e32 v3, v11, v29
	v_add_u32_e32 v29, 35, v44
	v_cndmask_b32_e64 v10, v214, v2, s[40:41]
	v_add_u32_e32 v2, 17, v44
	v_cmp_gt_u32_e64 s[40:41], 16, v2
	v_add_u32_e32 v2, 18, v44
	s_nop 0
	v_cndmask_b32_e64 v11, v214, v3, s[40:41]
	v_add_f32_e32 v3, v12, v30
	v_cmp_gt_u32_e64 s[40:41], 16, v2
	v_add_u32_e32 v2, 19, v44
	s_nop 0
	v_cndmask_b32_e64 v12, v214, v3, s[40:41]
	v_add_f32_e32 v3, v13, v31
	v_cmp_gt_u32_e64 s[40:41], 16, v2
	v_add_u32_e32 v2, 24, v44
	v_add_u32_e32 v31, 42, v44
	v_cndmask_b32_e64 v13, v214, v3, s[40:41]
	v_add_f32_e32 v3, v14, v32
	v_cmp_gt_u32_e64 s[40:41], 16, v2
	v_add_u32_e32 v2, 25, v44
	v_add_u32_e32 v32, 41, v44
	v_cndmask_b32_e64 v14, v214, v3, s[40:41]
	v_add_f32_e32 v3, v15, v33
	v_cmp_gt_u32_e64 s[40:41], 16, v2
	v_add_u32_e32 v2, 26, v44
	s_nop 0
	v_cndmask_b32_e64 v15, v214, v3, s[40:41]
	v_add_f32_e32 v3, v16, v34
	v_cmp_gt_u32_e64 s[40:41], 16, v2
	v_add_u32_e32 v2, 27, v44
	s_nop 0
	v_cndmask_b32_e64 v16, v214, v3, s[40:41]
	v_add_f32_e32 v3, v17, v35
	v_cmp_gt_u32_e64 s[40:41], 16, v2
	v_mov_b32_e32 v2, v81
	s_nop 0
	v_cndmask_b32_e64 v17, v214, v3, s[40:41]
	v_mov_b32_e32 v3, v82
	v_pk_add_f32 v[2:3], v[2:3], v[4:5]
	v_cmp_gt_u32_e64 s[40:41], 16, v8
	v_mov_b32_e32 v5, v84
	v_mov_b32_e32 v8, v39
	v_cndmask_b32_e64 v3, v214, v3, s[40:41]
	v_cmp_gt_u32_e64 s[40:41], 16, v9
	v_mov_b32_e32 v9, v40
	v_max3_f32 v6, v6, v20, v3
	v_cndmask_b32_e64 v2, v214, v2, s[40:41]
	v_max3_f32 v4, v22, v23, v2
	v_max3_f32 v4, v4, v25, v26
	v_max3_f32 v4, v4, v12, v13
	v_max3_f32 v30, v4, v16, v17
	v_mov_b32_e32 v4, v83
	v_pk_add_f32 v[4:5], v[4:5], v[8:9]
	v_cmp_gt_u32_e64 s[40:41], 16, v28
	v_mov_b32_e32 v8, v85
	v_mov_b32_e32 v9, v86
	v_cndmask_b32_e64 v5, v214, v5, s[40:41]
	v_cmp_gt_u32_e64 s[40:41], 16, v29
	v_mov_b32_e32 v28, v41
	v_mov_b32_e32 v29, v42
	v_cndmask_b32_e64 v4, v214, v4, s[40:41]
	v_max3_f32 v6, v6, v4, v24
	v_max3_f32 v6, v6, v7, v10
	v_pk_add_f32 v[8:9], v[8:9], v[28:29]
	v_cmp_gt_u32_e64 s[40:41], 16, v31
	v_max3_f32 v6, v6, v11, v14
	v_max3_f32 v6, v6, v15, v5
	v_cndmask_b32_e64 v9, v214, v9, s[40:41]
	v_cmp_gt_u32_e64 s[40:41], 16, v32
	v_max3_f32 v28, v30, v9, v27
	s_nop 0
	v_cndmask_b32_e64 v8, v214, v8, s[40:41]
	v_max3_f32 v6, v6, v8, v28
	v_mov_b32_e32 v28, v6
	s_nop 1
	v_permlane32_swap_b32_e32 v6, v28
	v_max_f32_e32 v6, v6, v28
	v_exp_f32_e64 v28, -v6
	v_add_f32_e32 v240, 0, v6
	v_xor_b32_e32 v112, 0x80000000, v240
	v_mov_b32_e32 v113, v112
	v_mov_b32_e32 v114, v112
	v_mov_b32_e32 v115, v112
	v_mov_b32_e32 v116, v112
	v_mov_b32_e32 v117, v112
	v_mov_b32_e32 v118, v112
	v_mov_b32_e32 v119, v112
	v_mov_b32_e32 v120, v112
	v_mov_b32_e32 v121, v112
	v_mov_b32_e32 v122, v112
	v_mov_b32_e32 v123, v112
	v_mov_b32_e32 v124, v112
	v_mov_b32_e32 v125, v112
	v_mov_b32_e32 v126, v112
	v_mov_b32_e32 v127, v112
	s_and_saveexec_b64 s[6:7], vcc
	v_lshl_add_u32 v29, v221, 2, s26
	ds_write_b32 v29, v28 offset:128
	s_or_b64 exec, exec, s[6:7]
	v_sub_f32_e32 v19, v19, v6
	v_pk_add_f32 v[2:3], v[2:3], v[6:7] op_sel_hi:[1,0] neg_lo:[0,1] neg_hi:[0,1]
	v_sub_f32_e32 v80, v20, v6
	v_sub_f32_e32 v20, v21, v6
	v_mov_b32_e32 v81, v2
	v_exp_f32_e32 v2, v19
	v_sub_f32_e32 v21, v22, v6
	v_pk_add_f32 v[4:5], v[4:5], v[6:7] op_sel_hi:[1,0] neg_lo:[0,1] neg_hi:[0,1]
	v_mov_b32_e32 v82, v3
	v_exp_f32_e32 v3, v20
	v_sub_f32_e32 v22, v23, v6
	v_sub_f32_e32 v7, v7, v6
	v_mov_b32_e32 v83, v4
	v_exp_f32_e32 v4, v21
	v_sub_f32_e32 v23, v24, v6
	v_pk_add_f32 v[8:9], v[8:9], v[6:7] op_sel_hi:[1,0] neg_lo:[0,1] neg_hi:[0,1]
	v_mov_b32_e32 v84, v5
	v_exp_f32_e32 v5, v22
	v_mov_b32_e32 v85, v8
	v_exp_f32_e32 v8, v23
	v_add_f32_e32 v19, 0, v2
	v_sub_f32_e32 v24, v25, v6
	v_exp_f32_e32 v7, v7
	v_add_f32_e32 v19, v3, v19
	v_sub_f32_e32 v25, v26, v6
	v_mov_b32_e32 v86, v9
	v_exp_f32_e32 v9, v24
	v_add_f32_e32 v19, v4, v19
	v_sub_f32_e32 v87, v27, v6
	v_sub_f32_e32 v10, v10, v6
	v_sub_f32_e32 v11, v11, v6
	v_sub_f32_e32 v12, v12, v6
	v_sub_f32_e32 v13, v13, v6
	v_sub_f32_e32 v14, v14, v6
	v_sub_f32_e32 v15, v15, v6
	v_sub_f32_e32 v16, v16, v6
	v_sub_f32_e32 v6, v17, v6
	v_exp_f32_e32 v17, v25
	v_add_f32_e32 v19, v5, v19
	v_exp_f32_e32 v10, v10
	v_add_f32_e32 v19, v8, v19
	v_exp_f32_e32 v11, v11
	v_add_f32_e32 v19, v7, v19
	v_exp_f32_e32 v12, v12
	v_add_f32_e32 v19, v9, v19
	v_exp_f32_e32 v13, v13
	v_add_f32_e32 v19, v17, v19
	v_exp_f32_e32 v14, v14
	v_add_f32_e32 v19, v10, v19
	v_exp_f32_e32 v15, v15
	v_add_f32_e32 v19, v11, v19
	v_exp_f32_e32 v16, v16
	v_add_f32_e32 v19, v12, v19
	v_exp_f32_e32 v6, v6
	v_add_f32_e32 v19, v13, v19
	v_add_f32_e32 v19, v14, v19
	v_add_f32_e32 v19, v15, v19
	v_add_f32_e32 v19, v16, v19
	v_cvt_pk_bf16_f32 v196, v2, v3
	v_cvt_pk_bf16_f32 v197, v4, v5
	v_cvt_pk_bf16_f32 v198, v8, v7
	v_cvt_pk_bf16_f32 v199, v9, v17
	v_cvt_pk_bf16_f32 v192, v10, v11
	v_cvt_pk_bf16_f32 v193, v12, v13
	v_cvt_pk_bf16_f32 v194, v14, v15
	v_cvt_pk_bf16_f32 v195, v16, v6
	v_mul_f32_e32 v158, 0, v28
	v_add_f32_e32 v144, v6, v19
	v_permlane32_swap_b32_e32 v196, v198
	v_permlane32_swap_b32_e32 v197, v199
	v_permlane32_swap_b32_e32 v192, v194
	v_permlane32_swap_b32_e32 v193, v195
	s_branch .LBB0_289

.LBB0_299:
	s_add_i32 s5, s69, -4
	s_add_i32 s8, s69, -3
	s_cmp_ge_i32 s5, s95
	s_cselect_b64 s[0:1], -1, 0
	s_cmp_lt_i32 s5, s70
	s_cselect_b64 s[6:7], -1, 0
	s_and_b64 s[0:1], s[0:1], s[6:7]
	s_cmp_ge_i32 s8, s95
	s_cselect_b64 s[6:7], -1, 0
	s_cmp_lt_i32 s8, s70
	s_cselect_b64 s[8:9], -1, 0
	s_and_b64 s[42:43], s[6:7], s[8:9]
	s_andn2_b64 vcc, exec, s[0:1]
	s_mov_b64 s[6:7], -1
	s_cbranch_vccz .LBB0_320
	v_mov_b64_e32 v[6:7], v[196:197]
	v_mov_b64_e32 v[2:3], v[192:193]
	v_mov_b64_e32 v[142:143], v[126:127]
	v_mov_b32_e32 v98, v15
	v_mov_b32_e32 v99, v206
	v_mov_b32_e32 v100, v207
	v_mov_b32_e32 v101, v208
	v_mov_b32_e32 v102, v209
	s_andn2_b64 vcc, exec, s[42:43]
	v_mov_b32_e32 v241, v158
	v_mov_b64_e32 v[8:9], v[198:199]
	v_mov_b64_e32 v[4:5], v[194:195]
	v_mov_b32_e32 v1, v240
	v_mov_b64_e32 v[140:141], v[124:125]
	v_mov_b64_e32 v[138:139], v[122:123]
	v_mov_b64_e32 v[136:137], v[120:121]
	v_mov_b64_e32 v[134:135], v[118:119]
	v_mov_b64_e32 v[132:133], v[116:117]
	v_mov_b64_e32 v[130:131], v[114:115]
	v_mov_b64_e32 v[128:129], v[112:113]
	v_mov_b32_e32 v145, v144
	s_cbranch_vccnz .LBB0_304
	s_lshl_b32 s0, s99, 14
	s_add_i32 s0, s0, 0
	s_add_i32 s0, s0, 0x10000
	v_add_u32_e32 v1, s0, v229
	v_add_u32_e32 v10, s0, v231
	v_add_u32_e32 v2, v1, v230
	v_add_u32_e32 v6, v10, v230
	v_add_u32_e32 v11, v1, v232
	ds_read_b128 v[2:5], v2
	ds_read_b128 v[6:9], v6
	v_add_u32_e32 v14, v10, v232
	ds_read_b128 v[10:13], v11
	ds_read_b128 v[146:149], v14
	s_waitcnt lgkmcnt(3)
	v_mfma_f32_32x32x16_bf16 v[128:143], v[2:5], v[160:163], v[112:127]
	v_add_u32_e32 v14, v1, v234
	ds_read_b128 v[150:153], v14
	s_waitcnt lgkmcnt(3)
	v_mfma_f32_32x32x16_bf16 v[96:111], v[6:9], v[160:163], v[112:127]
	ds_read_b128 v[2:5], v14 offset:8192
	s_waitcnt lgkmcnt(3)
	v_mfma_f32_32x32x16_bf16 v[128:143], v[10:13], v[164:167], v[128:143]
	v_add_u32_e32 v14, v1, v235
	ds_read_b128 v[6:9], v14
	s_waitcnt lgkmcnt(3)
	v_mfma_f32_32x32x16_bf16 v[96:111], v[146:149], v[164:167], v[96:111]
	ds_read_b128 v[10:13], v14 offset:8192
	s_waitcnt lgkmcnt(3)
	v_mfma_f32_32x32x16_bf16 v[128:143], v[150:153], v[168:171], v[128:143]
	v_add_u32_e32 v14, v1, v236
	ds_read_b128 v[146:149], v14
	s_waitcnt lgkmcnt(3)
	v_mfma_f32_32x32x16_bf16 v[96:111], v[2:5], v[168:171], v[96:111]
	ds_read_b128 v[150:153], v14 offset:8192
	s_waitcnt lgkmcnt(3)
	v_mfma_f32_32x32x16_bf16 v[128:143], v[6:9], v[172:175], v[128:143]
	v_add_u32_e32 v14, v1, v237
	ds_read_b128 v[2:5], v14
	s_waitcnt lgkmcnt(3)
	v_mfma_f32_32x32x16_bf16 v[96:111], v[10:13], v[172:175], v[96:111]
	ds_read_b128 v[6:9], v14 offset:8192
	s_waitcnt lgkmcnt(3)
	v_mfma_f32_32x32x16_bf16 v[128:143], v[146:149], v[176:179], v[128:143]
	v_add_u32_e32 v14, v1, v238
	ds_read_b128 v[10:13], v14
	s_waitcnt lgkmcnt(3)
	v_mfma_f32_32x32x16_bf16 v[96:111], v[150:153], v[176:179], v[96:111]
	ds_read_b128 v[146:149], v14 offset:8192
	s_waitcnt lgkmcnt(3)
	v_mfma_f32_32x32x16_bf16 v[128:143], v[2:5], v[180:183], v[128:143]
	v_add_u32_e32 v1, v1, v239
	ds_read_b128 v[150:153], v1
	s_waitcnt lgkmcnt(3)
	v_mfma_f32_32x32x16_bf16 v[96:111], v[6:9], v[180:183], v[96:111]
	ds_read_b128 v[2:5], v1 offset:8192
	s_waitcnt lgkmcnt(3)
	v_mfma_f32_32x32x16_bf16 v[128:143], v[10:13], v[184:187], v[128:143]
	s_waitcnt lgkmcnt(2)
	v_mfma_f32_32x32x16_bf16 v[96:111], v[146:149], v[184:187], v[96:111]
	s_waitcnt lgkmcnt(1)
	v_mfma_f32_32x32x16_bf16 v[128:143], v[150:153], v[188:191], v[128:143]
	s_waitcnt lgkmcnt(0)
	v_mfma_f32_32x32x16_bf16 v[96:111], v[2:5], v[188:191], v[96:111]
	v_mov_b32_e32 v1, v233
	s_nop 0
	v_lshl_add_u32 v6, v1, 2, s30
	ds_read2_b32 v[2:3], v6 offset1:1
	ds_read2_b32 v[4:5], v6 offset0:2 offset1:3
	ds_read2_b32 v[8:9], v6 offset0:8 offset1:9
	ds_read2_b32 v[14:15], v6 offset0:10 offset1:11
	ds_read2_b32 v[150:151], v6 offset0:16 offset1:17
	ds_read2_b32 v[152:153], v6 offset0:18 offset1:19
	ds_read2_b32 v[154:155], v6 offset0:24 offset1:25
	ds_read2_b32 v[156:157], v6 offset0:26 offset1:27
	ds_read2_b32 v[200:201], v6 offset0:32 offset1:33
	ds_read2_b32 v[202:203], v6 offset0:34 offset1:35
	ds_read2_b32 v[206:207], v6 offset0:40 offset1:41
	ds_read2_b32 v[208:209], v6 offset0:42 offset1:43
	s_waitcnt lgkmcnt(11)
	v_add_u32_e32 v1, v1, v227
	v_add_f32_e32 v2, v128, v2
	v_cmp_gt_u32_e32 vcc, 16, v1
	s_waitcnt lgkmcnt(10)
	s_waitcnt lgkmcnt(9)
	v_cndmask_b32_e32 v7, v214, v2, vcc
	v_and_b32_e32 v2, -16, v1
	s_waitcnt lgkmcnt(8)
	s_waitcnt lgkmcnt(7)
	s_waitcnt lgkmcnt(6)
	s_waitcnt lgkmcnt(5)
	s_waitcnt lgkmcnt(4)
	s_waitcnt lgkmcnt(3)
	v_cmp_eq_u32_e32 vcc, s96, v2
	v_add_f32_e32 v6, v96, v200
	v_add_u32_e32 v2, 1, v1
	v_cndmask_b32_e32 v10, v214, v6, vcc
	v_add_f32_e32 v3, v129, v3
	v_cmp_gt_u32_e32 vcc, 16, v2
	v_add_u32_e32 v2, 2, v1
	s_waitcnt lgkmcnt(2)
	s_waitcnt lgkmcnt(1)
	v_cndmask_b32_e32 v11, v214, v3, vcc
	v_add_f32_e32 v3, v130, v4
	v_cmp_gt_u32_e32 vcc, 16, v2
	v_add_u32_e32 v2, 3, v1
	s_waitcnt lgkmcnt(0)
	v_mov_b32_e32 v4, v201
	v_cndmask_b32_e32 v12, v214, v3, vcc
	v_add_f32_e32 v3, v131, v5
	v_cmp_gt_u32_e32 vcc, 16, v2
	v_add_u32_e32 v2, 8, v1
	v_mov_b32_e32 v5, v202
	v_cndmask_b32_e32 v13, v214, v3, vcc
	v_add_f32_e32 v3, v132, v8
	v_cmp_gt_u32_e32 vcc, 16, v2
	v_add_u32_e32 v2, 9, v1
	v_add_u32_e32 v8, 34, v1
	v_cndmask_b32_e32 v145, v214, v3, vcc
	v_add_f32_e32 v3, v133, v9
	v_cmp_gt_u32_e32 vcc, 16, v2
	v_add_u32_e32 v2, 10, v1
	v_add_u32_e32 v9, 33, v1
	v_cndmask_b32_e32 v146, v214, v3, vcc
	v_add_f32_e32 v3, v134, v14
	v_cmp_gt_u32_e32 vcc, 16, v2
	v_add_u32_e32 v2, 11, v1
	v_add_u32_e32 v14, 40, v1
	v_cndmask_b32_e32 v147, v214, v3, vcc
	v_add_f32_e32 v3, v135, v15
	v_cmp_gt_u32_e32 vcc, 16, v2
	v_add_u32_e32 v2, 43, v1
	v_add_u32_e32 v15, 35, v1
	v_cndmask_b32_e32 v148, v214, v3, vcc
	v_add_f32_e32 v3, v103, v209
	v_cmp_gt_u32_e32 vcc, 16, v2
	v_add_f32_e32 v2, v136, v150
	v_max_f32_e32 v6, v7, v11
	v_cndmask_b32_e32 v103, v214, v3, vcc
	v_cmp_lt_u32_e32 vcc, s97, v1
	v_add_f32_e32 v3, v137, v151
	s_nop 0
	v_cndmask_b32_e32 v149, v214, v2, vcc
	v_add_u32_e32 v2, 17, v1
	v_cmp_gt_u32_e32 vcc, 16, v2
	v_add_u32_e32 v2, 18, v1
	s_nop 0
	v_cndmask_b32_e32 v150, v214, v3, vcc
	v_add_f32_e32 v3, v138, v152
	v_cmp_gt_u32_e32 vcc, 16, v2
	v_add_u32_e32 v2, 19, v1
	s_nop 0
	v_cndmask_b32_e32 v151, v214, v3, vcc
	v_add_f32_e32 v3, v139, v153
	v_cmp_gt_u32_e32 vcc, 16, v2
	v_add_u32_e32 v2, 24, v1
	s_nop 0
	v_cndmask_b32_e32 v152, v214, v3, vcc
	v_add_f32_e32 v3, v140, v154
	v_cmp_gt_u32_e32 vcc, 16, v2
	v_add_u32_e32 v2, 25, v1
	s_nop 0
	v_cndmask_b32_e32 v153, v214, v3, vcc
	v_add_f32_e32 v3, v141, v155
	v_cmp_gt_u32_e32 vcc, 16, v2
	v_add_u32_e32 v2, 26, v1
	s_nop 0
	v_cndmask_b32_e32 v154, v214, v3, vcc
	v_add_f32_e32 v3, v142, v156
	v_cmp_gt_u32_e32 vcc, 16, v2
	v_add_u32_e32 v2, 27, v1
	s_nop 0
	v_cndmask_b32_e32 v155, v214, v3, vcc
	v_add_f32_e32 v3, v143, v157
	v_cmp_gt_u32_e32 vcc, 16, v2
	v_mov_b32_e32 v2, v97
	v_add_u32_e32 v97, 42, v1
	v_cndmask_b32_e32 v156, v214, v3, vcc
	v_mov_b32_e32 v3, v98
	v_pk_add_f32 v[2:3], v[2:3], v[4:5]
	v_cmp_gt_u32_e32 vcc, 16, v8
	v_mov_b32_e32 v5, v100
	v_mov_b32_e32 v8, v203
	v_cndmask_b32_e32 v3, v214, v3, vcc
	v_cmp_gt_u32_e32 vcc, 16, v9
	v_mov_b32_e32 v9, v206
	v_max3_f32 v6, v6, v10, v3
	v_cndmask_b32_e32 v2, v214, v2, vcc
	v_max3_f32 v4, v12, v13, v2
	v_max3_f32 v4, v4, v147, v148
	v_max3_f32 v4, v4, v151, v152
	v_max3_f32 v96, v4, v155, v156
	v_mov_b32_e32 v4, v99
	v_pk_add_f32 v[4:5], v[4:5], v[8:9]
	v_cmp_gt_u32_e32 vcc, 16, v14
	v_mov_b32_e32 v8, v101
	v_mov_b32_e32 v9, v102
	v_cndmask_b32_e32 v5, v214, v5, vcc
	v_cmp_gt_u32_e32 vcc, 16, v15
	v_mov_b32_e32 v14, v207
	v_mov_b32_e32 v15, v208
	v_cndmask_b32_e32 v4, v214, v4, vcc
	v_max3_f32 v6, v6, v4, v145
	v_max3_f32 v6, v6, v146, v149
	v_add_u32_e32 v1, 41, v1
	v_pk_add_f32 v[8:9], v[8:9], v[14:15]
	v_cmp_gt_u32_e32 vcc, 16, v97
	v_max3_f32 v6, v6, v150, v153
	v_max3_f32 v6, v6, v154, v5
	v_cndmask_b32_e32 v9, v214, v9, vcc
	v_cmp_gt_u32_e32 vcc, 16, v1
	v_max3_f32 v1, v96, v9, v103
	s_nop 0
	v_cndmask_b32_e32 v8, v214, v8, vcc
	v_max3_f32 v1, v6, v8, v1
	v_mov_b32_e32 v6, v1
	s_nop 1
	v_permlane32_swap_b32_e32 v1, v6
	v_max_f32_e32 v6, v1, v6
	v_exp_f32_e64 v97, -v6
	v_add_f32_e32 v1, v240, v6
	v_xor_b32_e32 v128, 0x80000000, v1
	v_mov_b32_e32 v129, v128
	v_mov_b32_e32 v130, v128
	v_mov_b32_e32 v131, v128
	v_mov_b32_e32 v132, v128
	v_mov_b32_e32 v133, v128
	v_mov_b32_e32 v134, v128
	v_mov_b32_e32 v135, v128
	v_mov_b32_e32 v136, v128
	v_mov_b32_e32 v137, v128
	v_mov_b32_e32 v138, v128
	v_mov_b32_e32 v139, v128
	v_mov_b32_e32 v140, v128
	v_mov_b32_e32 v141, v128
	v_mov_b32_e32 v142, v128
	v_mov_b32_e32 v143, v128
	s_and_saveexec_b64 s[6:7], s[40:41]
	ds_write_b32 v225, v97 offset:128
	s_or_b64 exec, exec, s[6:7]
	v_sub_f32_e32 v7, v7, v6
	v_sub_f32_e32 v96, v10, v6
	v_sub_f32_e32 v10, v11, v6
	v_pk_add_f32 v[14:15], v[2:3], v[6:7] op_sel_hi:[1,0] neg_lo:[0,1] neg_hi:[0,1]
	v_pk_add_f32 v[206:207], v[4:5], v[6:7] op_sel_hi:[1,0] neg_lo:[0,1] neg_hi:[0,1]
	v_pk_add_f32 v[208:209], v[8:9], v[6:7] op_sel_hi:[1,0] neg_lo:[0,1] neg_hi:[0,1]
	v_exp_f32_e32 v7, v7
	v_sub_f32_e32 v2, v12, v6
	v_exp_f32_e32 v10, v10
	v_sub_f32_e32 v3, v13, v6
	v_exp_f32_e32 v2, v2
	v_sub_f32_e32 v4, v145, v6
	v_sub_f32_e32 v5, v146, v6
	v_sub_f32_e32 v8, v147, v6
	v_sub_f32_e32 v9, v148, v6
	v_sub_f32_e32 v103, v103, v6
	v_sub_f32_e32 v11, v149, v6
	v_sub_f32_e32 v12, v150, v6
	v_sub_f32_e32 v13, v151, v6
	v_sub_f32_e32 v98, v152, v6
	v_sub_f32_e32 v99, v153, v6
	v_sub_f32_e32 v100, v154, v6
	v_sub_f32_e32 v101, v155, v6
	v_sub_f32_e32 v6, v156, v6
	v_exp_f32_e32 v3, v3
	v_exp_f32_e32 v4, v4
	v_exp_f32_e32 v102, v6
	v_add_f32_e32 v6, 0, v7
	v_exp_f32_e32 v5, v5
	v_add_f32_e32 v6, v10, v6
	v_mul_f32_e32 v241, v158, v97
	v_exp_f32_e32 v97, v8
	v_add_f32_e32 v6, v2, v6
	v_exp_f32_e32 v9, v9
	v_add_f32_e32 v6, v3, v6
	v_exp_f32_e32 v11, v11
	v_add_f32_e32 v6, v4, v6
	v_exp_f32_e32 v12, v12
	v_add_f32_e32 v6, v5, v6
	v_exp_f32_e32 v13, v13
	v_add_f32_e32 v6, v97, v6
	v_exp_f32_e32 v98, v98
	v_add_f32_e32 v6, v9, v6
	v_exp_f32_e32 v99, v99
	v_add_f32_e32 v6, v11, v6
	v_exp_f32_e32 v100, v100
	v_add_f32_e32 v6, v12, v6
	v_exp_f32_e32 v101, v101
	v_add_f32_e32 v6, v13, v6
	v_add_f32_e32 v6, v98, v6
	v_add_f32_e32 v6, v99, v6
	v_add_f32_e32 v6, v100, v6
	v_add_f32_e32 v6, v101, v6
	v_add_f32_e32 v145, v102, v6
	v_cvt_pk_bf16_f32 v6, v7, v10
	v_cvt_pk_bf16_f32 v7, v2, v3
	v_cvt_pk_bf16_f32 v8, v4, v5
	v_cvt_pk_bf16_f32 v9, v97, v9
	v_cvt_pk_bf16_f32 v2, v11, v12
	v_cvt_pk_bf16_f32 v3, v13, v98
	v_cvt_pk_bf16_f32 v4, v99, v100
	v_cvt_pk_bf16_f32 v5, v101, v102
	s_nop 0
	v_permlane32_swap_b32_e32 v6, v8
	v_permlane32_swap_b32_e32 v7, v9
	v_permlane32_swap_b32_e32 v2, v4
	v_permlane32_swap_b32_e32 v3, v5
	v_mov_b32_e32 v98, v15
	v_mov_b32_e32 v99, v206
	v_mov_b32_e32 v100, v207
	v_mov_b32_e32 v101, v208
	v_mov_b32_e32 v102, v209

.LBB0_309:
	s_add_i32 s1, s99, 1
	s_and_b32 s1, s1, 3
	s_cmp_ge_i32 s31, s95
	s_cselect_b64 s[8:9], -1, 0
	s_and_b64 s[8:9], s[36:37], s[8:9]
	s_cmp_lt_i32 s31, s70
	s_cselect_b64 s[12:13], -1, 0
	s_and_b64 s[42:43], s[8:9], s[12:13]
	s_mov_b64 s[8:9], -1
	s_and_b64 vcc, exec, s[6:7]
	s_cbranch_vccz .LBB0_315
	v_mov_b64_e32 v[198:199], v[8:9]
	v_mov_b64_e32 v[194:195], v[4:5]
	v_mov_b64_e32 v[112:113], v[128:129]
	s_andn2_b64 vcc, exec, s[42:43]
	v_mov_b32_e32 v158, v241
	v_mov_b64_e32 v[196:197], v[6:7]
	v_mov_b64_e32 v[192:193], v[2:3]
	v_mov_b32_e32 v240, v1
	v_mov_b64_e32 v[114:115], v[130:131]
	v_mov_b64_e32 v[116:117], v[132:133]
	v_mov_b64_e32 v[118:119], v[134:135]
	v_mov_b64_e32 v[120:121], v[136:137]
	v_mov_b64_e32 v[122:123], v[138:139]
	v_mov_b64_e32 v[124:125], v[140:141]
	v_mov_b64_e32 v[126:127], v[142:143]
	v_mov_b32_e32 v144, v145
	s_cbranch_vccnz .LBB0_314
	s_lshl_b32 s5, s1, 14
	s_add_i32 s5, s5, 0
	s_add_i32 s5, s5, 0x10000
	v_add_u32_e32 v97, s5, v229
	v_add_u32_e32 v80, s5, v231
	v_add_u32_e32 v10, v97, v230
	v_add_u32_e32 v81, v80, v230
	ds_read_b128 v[10:13], v10
	ds_read_b128 v[146:149], v81
	v_add_u32_e32 v81, v97, v232
	v_add_u32_e32 v80, v80, v232
	ds_read_b128 v[150:153], v81
	ds_read_b128 v[154:157], v80
	s_waitcnt lgkmcnt(3)
	v_mfma_f32_32x32x16_bf16 v[112:127], v[10:13], v[160:163], v[128:143]
	v_add_u32_e32 v80, v97, v234
	ds_read_b128 v[192:195], v80
	ds_read_b128 v[10:13], v80 offset:8192
	s_waitcnt lgkmcnt(4)
	v_mfma_f32_32x32x16_bf16 v[80:95], v[146:149], v[160:163], v[128:143]
	s_waitcnt lgkmcnt(3)
	v_mfma_f32_32x32x16_bf16 v[112:127], v[150:153], v[164:167], v[112:127]
	v_add_u32_e32 v144, v97, v235
	ds_read_b128 v[146:149], v144
	s_waitcnt lgkmcnt(3)
	v_mfma_f32_32x32x16_bf16 v[80:95], v[154:157], v[164:167], v[80:95]
	ds_read_b128 v[150:153], v144 offset:8192
	s_waitcnt lgkmcnt(3)
	v_mfma_f32_32x32x16_bf16 v[112:127], v[192:195], v[168:171], v[112:127]
	v_add_u32_e32 v144, v97, v236
	ds_read_b128 v[154:157], v144
	s_waitcnt lgkmcnt(3)
	v_mfma_f32_32x32x16_bf16 v[80:95], v[10:13], v[168:171], v[80:95]
	ds_read_b128 v[192:195], v144 offset:8192
	s_waitcnt lgkmcnt(3)
	v_mfma_f32_32x32x16_bf16 v[112:127], v[146:149], v[172:175], v[112:127]
	v_add_u32_e32 v144, v97, v237
	ds_read_b128 v[10:13], v144
	s_waitcnt lgkmcnt(3)
	v_mfma_f32_32x32x16_bf16 v[80:95], v[150:153], v[172:175], v[80:95]
	ds_read_b128 v[146:149], v144 offset:8192
	s_waitcnt lgkmcnt(3)
	v_mfma_f32_32x32x16_bf16 v[112:127], v[154:157], v[176:179], v[112:127]
	v_add_u32_e32 v144, v97, v238
	ds_read_b128 v[150:153], v144
	s_waitcnt lgkmcnt(3)
	v_mfma_f32_32x32x16_bf16 v[80:95], v[192:195], v[176:179], v[80:95]
	ds_read_b128 v[154:157], v144 offset:8192
	s_waitcnt lgkmcnt(3)
	v_mfma_f32_32x32x16_bf16 v[112:127], v[10:13], v[180:183], v[112:127]
	v_add_u32_e32 v97, v97, v239
	ds_read_b128 v[192:195], v97
	s_waitcnt lgkmcnt(3)
	v_mfma_f32_32x32x16_bf16 v[80:95], v[146:149], v[180:183], v[80:95]
	ds_read_b128 v[10:13], v97 offset:8192
	s_waitcnt lgkmcnt(3)
	v_mfma_f32_32x32x16_bf16 v[112:127], v[150:153], v[184:187], v[112:127]
	s_waitcnt lgkmcnt(2)
	v_mfma_f32_32x32x16_bf16 v[80:95], v[154:157], v[184:187], v[80:95]
	s_waitcnt lgkmcnt(1)
	v_mfma_f32_32x32x16_bf16 v[112:127], v[192:195], v[188:191], v[112:127]
	s_waitcnt lgkmcnt(0)
	v_mfma_f32_32x32x16_bf16 v[80:95], v[10:13], v[188:191], v[80:95]
	v_mov_b32_e32 v97, v233
	s_nop 0
	v_lshl_add_u32 v144, v97, 2, s30
	ds_read2_b32 v[10:11], v144 offset0:31 offset1:32
	ds_read2_b32 v[12:13], v144 offset0:33 offset1:34
	ds_read2_b32 v[148:149], v144 offset0:39 offset1:40
	ds_read2_b32 v[150:151], v144 offset0:41 offset1:42
	ds_read2_b32 v[152:153], v144 offset0:47 offset1:48
	ds_read2_b32 v[154:155], v144 offset0:49 offset1:50
	ds_read2_b32 v[156:157], v144 offset0:55 offset1:56
	ds_read2_b32 v[158:159], v144 offset0:57 offset1:58
	ds_read2_b32 v[192:193], v144 offset0:63 offset1:64
	ds_read2_b32 v[194:195], v144 offset0:65 offset1:66
	ds_read2_b32 v[196:197], v144 offset0:71 offset1:72
	ds_read2_b32 v[198:199], v144 offset0:73 offset1:74
	s_waitcnt lgkmcnt(11)
	v_add_u32_e32 v200, v97, v227
	v_add_f32_e32 v10, v112, v10
	v_cmp_gt_u32_e32 vcc, 16, v200
	s_waitcnt lgkmcnt(10)
	s_waitcnt lgkmcnt(9)
	v_cndmask_b32_e32 v97, v214, v10, vcc
	v_and_b32_e32 v10, -16, v200
	s_waitcnt lgkmcnt(8)
	s_waitcnt lgkmcnt(7)
	s_waitcnt lgkmcnt(6)
	s_waitcnt lgkmcnt(5)
	s_waitcnt lgkmcnt(4)
	s_waitcnt lgkmcnt(3)
	v_cmp_eq_u32_e32 vcc, s96, v10
	v_add_f32_e32 v80, v80, v192
	v_add_u32_e32 v10, 1, v200
	v_cndmask_b32_e32 v80, v214, v80, vcc
	v_add_f32_e32 v11, v113, v11
	v_cmp_gt_u32_e32 vcc, 16, v10
	v_add_u32_e32 v10, 2, v200
	s_waitcnt lgkmcnt(2)
	s_waitcnt lgkmcnt(1)
	v_cndmask_b32_e32 v144, v214, v11, vcc
	v_add_f32_e32 v11, v114, v12
	v_cmp_gt_u32_e32 vcc, 16, v10
	v_add_u32_e32 v10, 3, v200
	s_waitcnt lgkmcnt(0)
	v_add_u32_e32 v113, 34, v200
	v_cndmask_b32_e32 v146, v214, v11, vcc
	v_add_f32_e32 v11, v115, v13
	v_cmp_gt_u32_e32 vcc, 16, v10
	v_add_u32_e32 v10, 8, v200
	v_mov_b32_e32 v12, v193
	v_cndmask_b32_e32 v147, v214, v11, vcc
	v_add_f32_e32 v11, v116, v148
	v_cmp_gt_u32_e32 vcc, 16, v10
	v_add_u32_e32 v10, 9, v200
	v_mov_b32_e32 v13, v194
	v_cndmask_b32_e32 v148, v214, v11, vcc
	v_add_f32_e32 v11, v117, v149
	v_cmp_gt_u32_e32 vcc, 16, v10
	v_add_u32_e32 v10, 10, v200
	v_add_u32_e32 v114, 33, v200
	v_cndmask_b32_e32 v149, v214, v11, vcc
	v_add_f32_e32 v11, v118, v150
	v_cmp_gt_u32_e32 vcc, 16, v10
	v_add_u32_e32 v10, 11, v200
	v_max_f32_e32 v112, v97, v144
	v_cndmask_b32_e32 v150, v214, v11, vcc
	v_add_f32_e32 v11, v119, v151
	v_cmp_gt_u32_e32 vcc, 16, v10
	v_add_u32_e32 v10, 43, v200
	s_nop 0
	v_cndmask_b32_e32 v151, v214, v11, vcc
	v_add_f32_e32 v11, v87, v199
	v_cmp_gt_u32_e32 vcc, 16, v10
	v_add_f32_e32 v10, v120, v152
	s_nop 0
	v_cndmask_b32_e32 v87, v214, v11, vcc
	v_cmp_lt_u32_e32 vcc, s97, v200
	v_add_f32_e32 v11, v121, v153
	s_nop 0
	v_cndmask_b32_e32 v152, v214, v10, vcc
	v_add_u32_e32 v10, 17, v200
	v_cmp_gt_u32_e32 vcc, 16, v10
	v_add_u32_e32 v10, 18, v200
	s_nop 0
	v_cndmask_b32_e32 v153, v214, v11, vcc
	v_add_f32_e32 v11, v122, v154
	v_cmp_gt_u32_e32 vcc, 16, v10
	v_add_u32_e32 v10, 19, v200
	s_nop 0
	v_cndmask_b32_e32 v154, v214, v11, vcc
	v_add_f32_e32 v11, v123, v155
	v_cmp_gt_u32_e32 vcc, 16, v10
	v_add_u32_e32 v10, 24, v200
	s_nop 0
	v_cndmask_b32_e32 v155, v214, v11, vcc
	v_add_f32_e32 v11, v124, v156
	v_cmp_gt_u32_e32 vcc, 16, v10
	v_add_u32_e32 v10, 25, v200
	s_nop 0
	v_cndmask_b32_e32 v156, v214, v11, vcc
	v_add_f32_e32 v11, v125, v157
	v_cmp_gt_u32_e32 vcc, 16, v10
	v_add_u32_e32 v10, 26, v200
	s_nop 0
	v_cndmask_b32_e32 v157, v214, v11, vcc
	v_add_f32_e32 v11, v126, v158
	v_cmp_gt_u32_e32 vcc, 16, v10
	v_add_u32_e32 v10, 27, v200
	s_nop 0
	v_cndmask_b32_e32 v158, v214, v11, vcc
	v_add_f32_e32 v11, v127, v159
	v_cmp_gt_u32_e32 vcc, 16, v10
	v_mov_b32_e32 v10, v81
	s_nop 0
	v_cndmask_b32_e32 v159, v214, v11, vcc
	v_mov_b32_e32 v11, v82
	v_pk_add_f32 v[10:11], v[10:11], v[12:13]
	v_cmp_gt_u32_e32 vcc, 16, v113
	v_add_u32_e32 v113, 40, v200
	v_mov_b32_e32 v13, v84
	v_cndmask_b32_e32 v11, v214, v11, vcc
	v_cmp_gt_u32_e32 vcc, 16, v114
	v_max3_f32 v81, v112, v80, v11
	v_mov_b32_e32 v82, v195
	v_cndmask_b32_e32 v10, v214, v10, vcc
	v_max3_f32 v12, v146, v147, v10
	v_max3_f32 v12, v12, v150, v151
	v_max3_f32 v12, v12, v154, v155
	v_max3_f32 v112, v12, v158, v159
	v_mov_b32_e32 v12, v83
	v_mov_b32_e32 v83, v196
	v_add_u32_e32 v114, 35, v200
	v_pk_add_f32 v[12:13], v[12:13], v[82:83]
	v_cmp_gt_u32_e32 vcc, 16, v113
	v_add_u32_e32 v113, 42, v200
	v_mov_b32_e32 v82, v85
	v_cndmask_b32_e32 v13, v214, v13, vcc
	v_cmp_gt_u32_e32 vcc, 16, v114
	v_mov_b32_e32 v83, v86
	v_mov_b32_e32 v84, v197
	v_cndmask_b32_e32 v12, v214, v12, vcc
	v_max3_f32 v81, v81, v12, v148
	v_mov_b32_e32 v85, v198
	v_max3_f32 v81, v81, v149, v152
	v_add_u32_e32 v114, 41, v200
	v_pk_add_f32 v[82:83], v[82:83], v[84:85]
	v_cmp_gt_u32_e32 vcc, 16, v113
	v_max3_f32 v81, v81, v153, v156
	v_max3_f32 v81, v81, v157, v13
	v_cndmask_b32_e32 v85, v214, v83, vcc
	v_cmp_gt_u32_e32 vcc, 16, v114
	s_nop 1
	v_cndmask_b32_e32 v84, v214, v82, vcc
	v_max3_f32 v82, v112, v85, v87
	v_max3_f32 v81, v81, v84, v82
	v_mov_b32_e32 v82, v81
	s_nop 1
	v_permlane32_swap_b32_e32 v81, v82
	v_max_f32_e32 v82, v81, v82
	v_exp_f32_e64 v192, -v82
	v_add_f32_e32 v240, v1, v82
	v_xor_b32_e32 v112, 0x80000000, v240
	v_mov_b32_e32 v113, v112
	v_mov_b32_e32 v114, v112
	v_mov_b32_e32 v115, v112
	v_mov_b32_e32 v116, v112
	v_mov_b32_e32 v117, v112
	v_mov_b32_e32 v118, v112
	v_mov_b32_e32 v119, v112
	v_mov_b32_e32 v120, v112
	v_mov_b32_e32 v121, v112
	v_mov_b32_e32 v122, v112
	v_mov_b32_e32 v123, v112
	v_mov_b32_e32 v124, v112
	v_mov_b32_e32 v125, v112
	v_mov_b32_e32 v126, v112
	v_mov_b32_e32 v127, v112
	s_and_saveexec_b64 s[6:7], s[40:41]
	ds_write_b32 v225, v192 offset:128
	s_or_b64 exec, exec, s[6:7]
	v_sub_f32_e32 v97, v97, v82
	v_pk_add_f32 v[10:11], v[10:11], v[82:83] op_sel_hi:[1,0] neg_lo:[0,1] neg_hi:[0,1]
	v_sub_f32_e32 v144, v144, v82
	v_mov_b32_e32 v81, v10
	v_exp_f32_e32 v10, v97
	v_sub_f32_e32 v80, v80, v82
	v_sub_f32_e32 v193, v146, v82
	v_sub_f32_e32 v194, v147, v82
	v_pk_add_f32 v[12:13], v[12:13], v[82:83] op_sel_hi:[1,0] neg_lo:[0,1] neg_hi:[0,1]
	v_sub_f32_e32 v148, v148, v82
	v_sub_f32_e32 v149, v149, v82
	v_pk_add_f32 v[146:147], v[84:85], v[82:83] op_sel_hi:[1,0] neg_lo:[0,1] neg_hi:[0,1]
	v_sub_f32_e32 v150, v150, v82
	v_sub_f32_e32 v151, v151, v82
	v_sub_f32_e32 v87, v87, v82
	v_sub_f32_e32 v152, v152, v82
	v_sub_f32_e32 v153, v153, v82
	v_sub_f32_e32 v154, v154, v82
	v_sub_f32_e32 v155, v155, v82
	v_sub_f32_e32 v156, v156, v82
	v_sub_f32_e32 v157, v157, v82
	v_sub_f32_e32 v195, v158, v82
	v_sub_f32_e32 v159, v159, v82
	v_mov_b32_e32 v82, v11
	v_exp_f32_e32 v11, v144
	v_mov_b32_e32 v83, v12
	v_exp_f32_e32 v12, v193
	v_mov_b32_e32 v84, v13
	v_exp_f32_e32 v13, v194
	v_exp_f32_e32 v97, v148
	v_add_f32_e32 v144, 0, v10
	v_mov_b32_e32 v85, v146
	v_exp_f32_e32 v146, v149
	v_add_f32_e32 v144, v11, v144
	v_mov_b32_e32 v86, v147
	v_exp_f32_e32 v147, v150
	v_add_f32_e32 v144, v12, v144
	v_exp_f32_e32 v148, v151
	v_add_f32_e32 v144, v13, v144
	v_exp_f32_e32 v149, v152
	v_add_f32_e32 v144, v97, v144
	v_exp_f32_e32 v150, v153
	v_add_f32_e32 v144, v146, v144
	v_exp_f32_e32 v151, v154
	v_add_f32_e32 v144, v147, v144
	v_exp_f32_e32 v152, v155
	v_add_f32_e32 v144, v148, v144
	v_exp_f32_e32 v153, v156
	v_add_f32_e32 v144, v149, v144
	v_exp_f32_e32 v154, v157
	v_add_f32_e32 v144, v150, v144
	v_exp_f32_e32 v155, v195
	v_add_f32_e32 v144, v151, v144
	v_exp_f32_e32 v156, v159
	v_add_f32_e32 v144, v152, v144
	v_add_f32_e32 v144, v153, v144
	v_add_f32_e32 v144, v154, v144
	v_mul_f32_e32 v158, v241, v192
	v_add_f32_e32 v144, v155, v144
	v_cvt_pk_bf16_f32 v196, v10, v11
	v_cvt_pk_bf16_f32 v197, v12, v13
	v_cvt_pk_bf16_f32 v198, v97, v146
	v_cvt_pk_bf16_f32 v199, v147, v148
	v_cvt_pk_bf16_f32 v192, v149, v150
	v_cvt_pk_bf16_f32 v193, v151, v152
	v_cvt_pk_bf16_f32 v194, v153, v154
	v_cvt_pk_bf16_f32 v195, v155, v156
	v_add_f32_e32 v144, v156, v144
	v_permlane32_swap_b32_e32 v196, v198
	v_permlane32_swap_b32_e32 v197, v199
	v_permlane32_swap_b32_e32 v192, v194
	v_permlane32_swap_b32_e32 v193, v195

.LBB0_315:
	s_andn2_b64 vcc, exec, s[8:9]
	s_cbranch_vccnz .LBB0_292
	s_addk_i32 s0, 0x4000
	s_and_b32 s0, s0, 0xc000
	s_lshl_b32 s1, s1, 14
	s_add_i32 s1, s1, 0
	s_add_i32 s1, s1, 0x10000
	v_add_u32_e32 v15, s1, v229
	v_add_u32_e32 v80, s1, v231
	v_add_u32_e32 v10, v15, v230
	v_add_u32_e32 v81, v80, v230
	ds_read_b128 v[10:13], v10
	ds_read_b128 v[146:149], v81
	v_add_u32_e32 v81, v15, v232
	v_add_u32_e32 v80, v80, v232
	ds_read_b128 v[150:153], v81
	ds_read_b128 v[154:157], v80
	v_exp_f32_e32 v97, v14
	v_add_u32_e32 v14, v15, v234
	ds_read_b128 v[192:195], v14
	v_exp_f32_e32 v96, v96
	v_add_u32_e32 v159, s0, v228
	s_waitcnt lgkmcnt(4)
	v_mfma_f32_32x32x16_bf16 v[112:127], v[10:13], v[160:163], v[128:143]
	s_waitcnt lgkmcnt(3)
	v_mfma_f32_32x32x16_bf16 v[80:95], v[146:149], v[160:163], v[128:143]
	ds_read_b128 v[10:13], v14 offset:8192
	v_add_f32_e32 v14, v145, v96
	v_exp_f32_e32 v98, v98
	v_exp_f32_e32 v99, v99
	v_add_f32_e32 v14, v97, v14
	v_add_u32_e32 v148, v15, v235
	ds_read_b128 v[144:147], v148
	v_add_f32_e32 v14, v14, v98
	v_exp_f32_e32 v100, v100
	v_exp_f32_e32 v101, v101
	v_add_f32_e32 v14, v99, v14
	s_waitcnt lgkmcnt(4)
	v_mfma_f32_32x32x16_bf16 v[112:127], v[150:153], v[164:167], v[112:127]
	s_waitcnt lgkmcnt(3)
	v_mfma_f32_32x32x16_bf16 v[80:95], v[154:157], v[164:167], v[80:95]
	ds_read_b128 v[148:151], v148 offset:8192
	v_add_f32_e32 v14, v14, v100
	v_exp_f32_e32 v102, v102
	v_exp_f32_e32 v103, v103
	v_add_f32_e32 v14, v101, v14
	v_add_u32_e32 v156, v15, v236
	ds_read_b128 v[152:155], v156
	v_add_f32_e32 v14, v14, v102
	v_add_f32_e32 v14, v103, v14
	s_waitcnt lgkmcnt(4)
	v_mfma_f32_32x32x16_bf16 v[112:127], v[192:195], v[168:171], v[112:127]
	s_waitcnt lgkmcnt(3)
	v_mfma_f32_32x32x16_bf16 v[80:95], v[10:13], v[168:171], v[80:95]
	ds_read_b128 v[192:195], v156 offset:8192
	v_cvt_pk_bf16_f32 v10, v96, v97
	v_cvt_pk_bf16_f32 v11, v98, v99
	v_add_u32_e32 v156, v15, v237
	ds_read_b128 v[196:199], v156
	s_waitcnt lgkmcnt(4)
	v_mfma_f32_32x32x16_bf16 v[112:127], v[144:147], v[172:175], v[112:127]
	v_cvt_pk_bf16_f32 v12, v100, v101
	v_cvt_pk_bf16_f32 v13, v102, v103
	s_waitcnt lgkmcnt(3)
	v_mfma_f32_32x32x16_bf16 v[80:95], v[148:151], v[172:175], v[80:95]
	ds_read_b128 v[144:147], v156 offset:8192
	v_permlane32_swap_b32_e32 v10, v12
	v_permlane32_swap_b32_e32 v11, v13
	v_add_u32_e32 v156, v15, v238
	ds_read_b128 v[148:151], v156
	s_waitcnt lgkmcnt(4)
	v_mfma_f32_32x32x16_bf16 v[112:127], v[152:155], v[176:179], v[112:127]
	v_mov_b32_e32 v152, v14
	s_nop 1
	v_permlane32_swap_b32_e32 v14, v152
	v_add_f32_e32 v14, v14, v152
	v_add_f32_e32 v158, v241, v14
	s_waitcnt lgkmcnt(3)
	v_mfma_f32_32x32x16_bf16 v[80:95], v[192:195], v[176:179], v[80:95]
	ds_read_b128 v[152:155], v156 offset:8192
	v_add_u32_e32 v14, v15, v239
	ds_read_b128 v[192:195], v14
	s_waitcnt lgkmcnt(4)
	v_mfma_f32_32x32x16_bf16 v[112:127], v[196:199], v[180:183], v[112:127]
	s_waitcnt lgkmcnt(3)
	v_mfma_f32_32x32x16_bf16 v[80:95], v[144:147], v[180:183], v[80:95]
	ds_read_b128 v[196:199], v14 offset:8192
	s_waitcnt lgkmcnt(3)
	v_mfma_f32_32x32x16_bf16 v[112:127], v[148:151], v[184:187], v[112:127]
	s_waitcnt lgkmcnt(2)
	v_mfma_f32_32x32x16_bf16 v[80:95], v[152:155], v[184:187], v[80:95]
	ds_read_b64_tr_b16 v[144:145], v159
	ds_read_b64_tr_b16 v[146:147], v159 offset:2048
	ds_read_b64_tr_b16 v[148:149], v159 offset:512
	ds_read_b64_tr_b16 v[150:151], v159 offset:2560
	s_waitcnt lgkmcnt(5)
	v_mfma_f32_32x32x16_bf16 v[112:127], v[192:195], v[188:191], v[112:127]
	s_waitcnt lgkmcnt(4)
	v_mfma_f32_32x32x16_bf16 v[80:95], v[196:199], v[188:191], v[80:95]
	ds_read_b64_tr_b16 v[152:153], v159 offset:1024
	ds_read_b64_tr_b16 v[154:155], v159 offset:3072
	s_waitcnt lgkmcnt(4)
	v_mfma_f32_32x32x16_bf16 v[64:79], v[6:9], v[144:147], v[64:79]
	ds_read_b64_tr_b16 v[206:207], v159 offset:1536
	ds_read_b64_tr_b16 v[208:209], v159 offset:3584
	s_waitcnt lgkmcnt(4)
	v_mfma_f32_32x32x16_bf16 v[48:63], v[6:9], v[148:151], v[48:63]
	ds_read_b64_tr_b16 v[200:201], v159 offset:4096
	ds_read_b64_tr_b16 v[202:203], v159 offset:6144
	s_waitcnt lgkmcnt(4)
	v_mfma_f32_32x32x16_bf16 v[32:47], v[6:9], v[152:155], v[32:47]
	ds_read_b64_tr_b16 v[196:197], v159 offset:4608
	ds_read_b64_tr_b16 v[198:199], v159 offset:6656
	s_waitcnt lgkmcnt(4)
	v_mfma_f32_32x32x16_bf16 v[16:31], v[6:9], v[206:209], v[16:31]
	ds_read_b64_tr_b16 v[192:193], v159 offset:5120
	ds_read_b64_tr_b16 v[194:195], v159 offset:7168
	v_mov_b32_e32 v6, v233
	s_nop 0
	v_lshl_add_u32 v206, v6, 2, s30
	v_add_u32_e32 v207, v6, v227
	ds_read2_b32 v[144:145], v206 offset0:31 offset1:32
	ds_read2_b32 v[146:147], v206 offset0:33 offset1:34
	ds_read2_b32 v[148:149], v206 offset0:39 offset1:40
	ds_read2_b32 v[152:153], v206 offset0:41 offset1:42
	ds_read2_b32 v[150:151], v206 offset0:47 offset1:48
	ds_read2_b32 v[14:15], v206 offset0:49 offset1:50
	ds_read2_b32 v[8:9], v206 offset0:55 offset1:56
	ds_read2_b32 v[6:7], v206 offset0:57 offset1:58
	ds_read2_b32 v[154:155], v206 offset0:63 offset1:64
	ds_read2_b32 v[156:157], v206 offset0:65 offset1:66
	ds_read2_b32 v[208:209], v206 offset0:71 offset1:72
	ds_read2_b32 v[210:211], v206 offset0:73 offset1:74
	v_cndmask_b32_e64 v212, v216, v207, s[42:43]
	s_waitcnt lgkmcnt(11)
	s_waitcnt lgkmcnt(10)
	s_waitcnt lgkmcnt(9)
	s_waitcnt lgkmcnt(8)
	s_waitcnt lgkmcnt(7)
	s_waitcnt lgkmcnt(6)
	s_waitcnt lgkmcnt(5)
	s_waitcnt lgkmcnt(4)
	s_waitcnt lgkmcnt(3)
	v_and_b32_e32 v206, -16, v212
	v_cmp_eq_u32_e32 vcc, s96, v206
	v_add_f32_e32 v80, v80, v154
	v_add_u32_e32 v154, 1, v212
	v_cndmask_b32_e32 v80, v214, v80, vcc
	v_cmp_gt_u32_e32 vcc, 16, v212
	v_cmp_gt_u32_e64 s[42:43], 16, v154
	v_pk_add_f32 v[112:113], v[112:113], v[144:145]
	s_waitcnt lgkmcnt(2)
	s_waitcnt lgkmcnt(1)
	v_cndmask_b32_e64 v206, v214, v113, s[42:43]
	v_cndmask_b32_e32 v207, v214, v112, vcc
	v_add_u32_e32 v112, 34, v212
	v_add_u32_e32 v113, 33, v212
	v_cmp_gt_u32_e32 vcc, 16, v113
	v_cmp_gt_u32_e64 s[42:43], 16, v112
	v_mov_b32_e32 v112, v81
	v_mov_b32_e32 v113, v82
	v_mov_b32_e32 v144, v155
	v_mov_b32_e32 v145, v156
	v_pk_add_f32 v[112:113], v[112:113], v[144:145]
	s_waitcnt lgkmcnt(0)
	v_pk_add_f32 v[14:15], v[122:123], v[14:15]
	v_cndmask_b32_e64 v82, v214, v113, s[42:43]
	v_cndmask_b32_e32 v81, v214, v112, vcc
	v_add_u32_e32 v112, 3, v212
	v_add_u32_e32 v113, 2, v212
	v_cmp_gt_u32_e32 vcc, 16, v113
	v_cmp_gt_u32_e64 s[42:43], 16, v112
	v_pk_add_f32 v[112:113], v[114:115], v[146:147]
	v_mov_b32_e32 v114, v157
	v_cndmask_b32_e64 v145, v214, v113, s[42:43]
	v_cndmask_b32_e32 v144, v214, v112, vcc
	v_add_u32_e32 v112, 40, v212
	v_add_u32_e32 v113, 35, v212
	v_cmp_gt_u32_e32 vcc, 16, v113
	v_cmp_gt_u32_e64 s[42:43], 16, v112
	v_mov_b32_e32 v112, v83
	v_mov_b32_e32 v113, v84
	v_mov_b32_e32 v115, v208
	v_pk_add_f32 v[112:113], v[112:113], v[114:115]
	v_mov_b32_e32 v114, v209
	v_cndmask_b32_e64 v84, v214, v113, s[42:43]
	v_cndmask_b32_e32 v83, v214, v112, vcc
	v_add_u32_e32 v112, 9, v212
	v_add_u32_e32 v113, 8, v212
	v_cmp_gt_u32_e32 vcc, 16, v113
	v_cmp_gt_u32_e64 s[42:43], 16, v112
	v_pk_add_f32 v[112:113], v[116:117], v[148:149]
	v_mov_b32_e32 v115, v210
	v_cndmask_b32_e64 v147, v214, v113, s[42:43]
	v_cndmask_b32_e32 v146, v214, v112, vcc
	v_add_u32_e32 v112, 42, v212
	v_add_u32_e32 v113, 41, v212
	v_cmp_gt_u32_e32 vcc, 16, v113
	v_cmp_gt_u32_e64 s[42:43], 16, v112
	v_mov_b32_e32 v112, v85
	v_mov_b32_e32 v113, v86
	v_pk_add_f32 v[112:113], v[112:113], v[114:115]
	v_add_f32_e32 v87, v87, v211
	v_cndmask_b32_e64 v86, v214, v113, s[42:43]
	v_cndmask_b32_e32 v85, v214, v112, vcc
	v_add_u32_e32 v112, 11, v212
	v_add_u32_e32 v113, 10, v212
	v_cmp_gt_u32_e32 vcc, 16, v113
	v_cmp_gt_u32_e64 s[42:43], 16, v112
	v_pk_add_f32 v[112:113], v[118:119], v[152:153]
	v_pk_add_f32 v[8:9], v[124:125], v[8:9]
	v_cndmask_b32_e32 v148, v214, v112, vcc
	v_add_u32_e32 v112, 43, v212
	v_cmp_gt_u32_e32 vcc, 16, v112
	v_add_u32_e32 v112, 17, v212
	v_cndmask_b32_e64 v149, v214, v113, s[42:43]
	v_cmp_gt_u32_e64 s[42:43], 16, v112
	v_pk_add_f32 v[112:113], v[120:121], v[150:151]
	v_cndmask_b32_e32 v87, v214, v87, vcc
	v_cmp_lt_u32_e32 vcc, s97, v212
	v_cndmask_b32_e64 v151, v214, v113, s[42:43]
	v_add_u32_e32 v113, 18, v212
	v_cndmask_b32_e32 v150, v214, v112, vcc
	v_add_u32_e32 v112, 19, v212
	v_cmp_gt_u32_e32 vcc, 16, v113
	v_cmp_gt_u32_e64 s[42:43], 16, v112
	v_pk_add_f32 v[6:7], v[126:127], v[6:7]
	v_cndmask_b32_e32 v152, v214, v14, vcc
	v_add_u32_e32 v14, 25, v212
	v_cndmask_b32_e64 v153, v214, v15, s[42:43]
	v_add_u32_e32 v15, 24, v212
	v_cmp_gt_u32_e64 s[42:43], 16, v14
	v_cmp_gt_u32_e32 vcc, 16, v15
	s_nop 0
	v_cndmask_b32_e64 v155, v214, v9, s[42:43]
	v_add_u32_e32 v9, 26, v212
	v_cndmask_b32_e32 v154, v214, v8, vcc
	v_add_u32_e32 v8, 27, v212
	v_cmp_gt_u32_e32 vcc, 16, v9
	v_cmp_gt_u32_e64 s[42:43], 16, v8
	s_nop 0
	v_cndmask_b32_e32 v156, v214, v6, vcc
	v_max_f32_e32 v6, v207, v206
	v_cndmask_b32_e64 v157, v214, v7, s[42:43]
	v_max3_f32 v7, v144, v145, v81
	v_max3_f32 v6, v6, v80, v82
	v_max3_f32 v6, v6, v83, v146
	v_max3_f32 v7, v7, v148, v149
	v_max3_f32 v6, v6, v147, v150
	v_max3_f32 v7, v7, v152, v153
	v_max3_f32 v6, v6, v151, v154
	v_max3_f32 v7, v7, v156, v157
	v_max3_f32 v6, v6, v155, v84
	v_max3_f32 v7, v7, v86, v87
	v_max3_f32 v6, v6, v85, v7
	v_mov_b32_e32 v7, v6
	s_nop 1
	v_permlane32_swap_b32_e32 v6, v7
	v_max_f32_e32 v6, v6, v7
	v_cmp_lt_f32_e32 vcc, s92, v6
	s_cmp_lg_u64 vcc, 0
	s_cselect_b64 s[6:7], -1, 0
	s_cbranch_vccnz .LBB0_328
	v_mov_b64_e32 v[112:113], v[128:129]
	v_mov_b64_e32 v[114:115], v[130:131]
	v_mov_b64_e32 v[116:117], v[132:133]
	v_mov_b64_e32 v[118:119], v[134:135]
	v_mov_b64_e32 v[120:121], v[136:137]
	v_mov_b64_e32 v[122:123], v[138:139]
	v_mov_b64_e32 v[124:125], v[140:141]
	v_mov_b64_e32 v[126:127], v[142:143]
	v_mov_b32_e32 v240, v1

.LBB0_321:
	s_lshl_b32 s1, s99, 14
	s_add_i32 s1, s1, 0
	s_add_i32 s1, s1, 0x10000
	v_add_u32_e32 v1, s1, v229
	v_add_u32_e32 v10, s1, v231
	v_add_u32_e32 v2, v1, v230
	v_add_u32_e32 v6, v10, v230
	v_add_u32_e32 v11, v1, v232
	ds_read_b128 v[2:5], v2
	ds_read_b128 v[6:9], v6
	v_add_u32_e32 v14, v10, v232
	ds_read_b128 v[10:13], v11
	ds_read_b128 v[146:149], v14
	v_add_u32_e32 v14, v1, v234
	ds_read_b128 v[150:153], v14
	v_exp_f32_e32 v80, v80
	v_exp_f32_e32 v81, v81
	v_add_u32_e32 v242, s0, v228
	s_waitcnt lgkmcnt(4)
	v_mfma_f32_32x32x16_bf16 v[128:143], v[2:5], v[160:163], v[112:127]
	s_waitcnt lgkmcnt(3)
	v_mfma_f32_32x32x16_bf16 v[96:111], v[6:9], v[160:163], v[112:127]
	ds_read_b128 v[2:5], v14 offset:8192
	v_add_f32_e32 v14, v144, v80
	v_exp_f32_e32 v82, v82
	v_exp_f32_e32 v83, v83
	v_add_f32_e32 v14, v81, v14
	v_add_u32_e32 v15, v1, v235
	ds_read_b128 v[6:9], v15
	s_waitcnt lgkmcnt(4)
	v_mfma_f32_32x32x16_bf16 v[128:143], v[10:13], v[164:167], v[128:143]
	v_add_f32_e32 v10, v14, v82
	v_exp_f32_e32 v84, v84
	v_exp_f32_e32 v85, v85
	v_add_f32_e32 v14, v83, v10
	s_waitcnt lgkmcnt(3)
	v_mfma_f32_32x32x16_bf16 v[96:111], v[146:149], v[164:167], v[96:111]
	ds_read_b128 v[10:13], v15 offset:8192
	v_add_f32_e32 v14, v14, v84
	v_exp_f32_e32 v86, v86
	v_exp_f32_e32 v87, v87
	v_add_f32_e32 v14, v85, v14
	v_add_u32_e32 v15, v1, v236
	ds_read_b128 v[144:147], v15
	v_add_f32_e32 v14, v14, v86
	v_add_f32_e32 v14, v87, v14
	s_waitcnt lgkmcnt(4)
	v_mfma_f32_32x32x16_bf16 v[128:143], v[150:153], v[168:171], v[128:143]
	s_waitcnt lgkmcnt(3)
	v_mfma_f32_32x32x16_bf16 v[96:111], v[2:5], v[168:171], v[96:111]
	ds_read_b128 v[148:151], v15 offset:8192
	v_cvt_pk_bf16_f32 v2, v80, v81
	v_cvt_pk_bf16_f32 v3, v82, v83
	v_add_u32_e32 v15, v1, v237
	ds_read_b128 v[152:155], v15
	s_waitcnt lgkmcnt(4)
	v_mfma_f32_32x32x16_bf16 v[128:143], v[6:9], v[172:175], v[128:143]
	v_cvt_pk_bf16_f32 v4, v84, v85
	v_cvt_pk_bf16_f32 v5, v86, v87
	s_waitcnt lgkmcnt(3)
	v_mfma_f32_32x32x16_bf16 v[96:111], v[10:13], v[172:175], v[96:111]
	ds_read_b128 v[6:9], v15 offset:8192
	v_permlane32_swap_b32_e32 v2, v4
	v_permlane32_swap_b32_e32 v3, v5
	v_add_u32_e32 v15, v1, v238
	ds_read_b128 v[10:13], v15
	s_waitcnt lgkmcnt(4)
	v_mfma_f32_32x32x16_bf16 v[128:143], v[144:147], v[176:179], v[128:143]
	v_mov_b32_e32 v144, v14
	s_nop 1
	v_permlane32_swap_b32_e32 v14, v144
	v_add_f32_e32 v14, v14, v144
	v_add_f32_e32 v241, v158, v14
	s_waitcnt lgkmcnt(3)
	v_mfma_f32_32x32x16_bf16 v[96:111], v[148:151], v[176:179], v[96:111]
	ds_read_b128 v[144:147], v15 offset:8192
	v_add_u32_e32 v1, v1, v239
	ds_read_b128 v[148:151], v1
	s_waitcnt lgkmcnt(4)
	v_mfma_f32_32x32x16_bf16 v[128:143], v[152:155], v[180:183], v[128:143]
	s_waitcnt lgkmcnt(3)
	v_mfma_f32_32x32x16_bf16 v[96:111], v[6:9], v[180:183], v[96:111]
	ds_read_b128 v[152:155], v1 offset:8192
	s_waitcnt lgkmcnt(3)
	v_mfma_f32_32x32x16_bf16 v[128:143], v[10:13], v[184:187], v[128:143]
	s_waitcnt lgkmcnt(2)
	v_mfma_f32_32x32x16_bf16 v[96:111], v[144:147], v[184:187], v[96:111]
	ds_read_b64_tr_b16 v[6:7], v242
	ds_read_b64_tr_b16 v[8:9], v242 offset:2048
	ds_read_b64_tr_b16 v[10:11], v242 offset:512
	ds_read_b64_tr_b16 v[12:13], v242 offset:2560
	s_waitcnt lgkmcnt(5)
	v_mfma_f32_32x32x16_bf16 v[128:143], v[148:151], v[188:191], v[128:143]
	s_waitcnt lgkmcnt(4)
	v_mfma_f32_32x32x16_bf16 v[96:111], v[152:155], v[188:191], v[96:111]
	ds_read_b64_tr_b16 v[144:145], v242 offset:1024
	ds_read_b64_tr_b16 v[146:147], v242 offset:3072
	s_waitcnt lgkmcnt(4)
	v_mfma_f32_32x32x16_bf16 v[64:79], v[196:199], v[6:9], v[64:79]
	ds_read_b64_tr_b16 v[148:149], v242 offset:1536
	ds_read_b64_tr_b16 v[150:151], v242 offset:3584
	s_waitcnt lgkmcnt(4)
	v_mfma_f32_32x32x16_bf16 v[48:63], v[196:199], v[10:13], v[48:63]
	ds_read_b64_tr_b16 v[200:201], v242 offset:4096
	ds_read_b64_tr_b16 v[202:203], v242 offset:6144
	s_waitcnt lgkmcnt(4)
	v_mfma_f32_32x32x16_bf16 v[32:47], v[196:199], v[144:147], v[32:47]
	ds_read_b64_tr_b16 v[10:11], v242 offset:4608
	ds_read_b64_tr_b16 v[12:13], v242 offset:6656
	s_waitcnt lgkmcnt(4)
	v_mfma_f32_32x32x16_bf16 v[16:31], v[196:199], v[148:151], v[16:31]
	ds_read_b64_tr_b16 v[6:7], v242 offset:5120
	ds_read_b64_tr_b16 v[8:9], v242 offset:7168
	v_mov_b32_e32 v1, v233
	s_nop 0
	v_lshl_add_u32 v196, v1, 2, s30
	v_add_u32_e32 v1, v1, v227
	ds_read2_b32 v[14:15], v196 offset1:1
	ds_read2_b32 v[146:147], v196 offset0:2 offset1:3
	ds_read2_b32 v[148:149], v196 offset0:8 offset1:9
	ds_read2_b32 v[150:151], v196 offset0:10 offset1:11
	ds_read2_b32 v[152:153], v196 offset0:16 offset1:17
	ds_read2_b32 v[154:155], v196 offset0:18 offset1:19
	ds_read2_b32 v[156:157], v196 offset0:24 offset1:25
	ds_read2_b32 v[144:145], v196 offset0:26 offset1:27
	ds_read2_b32 v[158:159], v196 offset0:32 offset1:33
	ds_read2_b32 v[198:199], v196 offset0:34 offset1:35
	ds_read2_b32 v[208:209], v196 offset0:40 offset1:41
	ds_read2_b32 v[210:211], v196 offset0:42 offset1:43
	v_cndmask_b32_e64 v1, v216, v1, s[42:43]
	s_waitcnt lgkmcnt(11)
	s_waitcnt lgkmcnt(10)
	s_waitcnt lgkmcnt(9)
	s_waitcnt lgkmcnt(8)
	s_waitcnt lgkmcnt(7)
	s_waitcnt lgkmcnt(6)
	s_waitcnt lgkmcnt(5)
	s_waitcnt lgkmcnt(4)
	s_waitcnt lgkmcnt(3)
	v_and_b32_e32 v196, -16, v1
	v_cmp_eq_u32_e32 vcc, s96, v196
	v_add_f32_e32 v96, v96, v158
	v_add_u32_e32 v158, 1, v1
	v_cndmask_b32_e32 v96, v214, v96, vcc
	v_cmp_gt_u32_e32 vcc, 16, v1
	v_cmp_gt_u32_e64 s[46:47], 16, v158
	v_pk_add_f32 v[14:15], v[128:129], v[14:15]
	s_waitcnt lgkmcnt(2)
	s_waitcnt lgkmcnt(1)
	v_cndmask_b32_e64 v196, v214, v15, s[46:47]
	v_cndmask_b32_e32 v197, v214, v14, vcc
	v_add_u32_e32 v14, 34, v1
	v_add_u32_e32 v15, 33, v1
	v_cmp_gt_u32_e32 vcc, 16, v15
	v_cmp_gt_u32_e64 s[46:47], 16, v14
	v_mov_b32_e32 v14, v97
	v_mov_b32_e32 v15, v98
	v_mov_b32_e32 v128, v159
	v_mov_b32_e32 v129, v198
	v_pk_add_f32 v[14:15], v[14:15], v[128:129]
	v_add_u32_e32 v97, 3, v1
	v_add_u32_e32 v98, 2, v1
	v_cndmask_b32_e64 v15, v214, v15, s[46:47]
	v_cndmask_b32_e32 v14, v214, v14, vcc
	v_cmp_gt_u32_e32 vcc, 16, v98
	v_cmp_gt_u32_e64 s[46:47], 16, v97
	v_pk_add_f32 v[128:129], v[130:131], v[146:147]
	v_add_u32_e32 v98, 35, v1
	v_cndmask_b32_e64 v147, v214, v129, s[46:47]
	v_cndmask_b32_e32 v146, v214, v128, vcc
	v_cmp_gt_u32_e32 vcc, 16, v98
	v_mov_b32_e32 v98, v99
	v_mov_b32_e32 v99, v100
	v_mov_b32_e32 v128, v199
	v_mov_b32_e32 v129, v208
	v_add_u32_e32 v97, 40, v1
	v_pk_add_f32 v[98:99], v[98:99], v[128:129]
	v_cmp_gt_u32_e64 s[46:47], 16, v97
	v_cndmask_b32_e32 v206, v214, v98, vcc
	v_add_u32_e32 v98, 8, v1
	v_cndmask_b32_e64 v207, v214, v99, s[46:47]
	v_add_u32_e32 v97, 9, v1
	v_cmp_gt_u32_e32 vcc, 16, v98
	v_pk_add_f32 v[98:99], v[132:133], v[148:149]
	v_cmp_gt_u32_e64 s[46:47], 16, v97
	v_cndmask_b32_e32 v148, v214, v98, vcc
	v_add_u32_e32 v98, 41, v1
	s_waitcnt lgkmcnt(0)
	v_cndmask_b32_e64 v149, v214, v99, s[46:47]
	v_cmp_gt_u32_e32 vcc, 16, v98
	v_mov_b32_e32 v98, v101
	v_mov_b32_e32 v99, v102
	v_mov_b32_e32 v100, v209
	v_mov_b32_e32 v101, v210
	v_add_u32_e32 v97, 42, v1
	v_pk_add_f32 v[98:99], v[98:99], v[100:101]
	v_cmp_gt_u32_e64 s[46:47], 16, v97
	v_cndmask_b32_e32 v208, v214, v98, vcc
	v_add_u32_e32 v97, 11, v1
	v_add_u32_e32 v98, 10, v1
	v_cndmask_b32_e64 v209, v214, v99, s[46:47]
	v_cmp_gt_u32_e32 vcc, 16, v98
	v_cmp_gt_u32_e64 s[46:47], 16, v97
	v_pk_add_f32 v[98:99], v[134:135], v[150:151]
	v_add_u32_e32 v97, 43, v1
	v_cndmask_b32_e32 v150, v214, v98, vcc
	v_cmp_gt_u32_e32 vcc, 16, v97
	v_add_f32_e32 v97, v103, v211
	v_cndmask_b32_e64 v151, v214, v99, s[46:47]
	v_cndmask_b32_e32 v103, v214, v97, vcc
	v_add_u32_e32 v97, 17, v1
	v_cmp_lt_u32_e32 vcc, s97, v1
	v_pk_add_f32 v[98:99], v[136:137], v[152:153]
	v_cmp_gt_u32_e64 s[46:47], 16, v97
	v_cndmask_b32_e32 v152, v214, v98, vcc
	v_add_u32_e32 v98, 18, v1
	v_cndmask_b32_e64 v153, v214, v99, s[46:47]
	v_add_u32_e32 v97, 19, v1
	v_cmp_gt_u32_e32 vcc, 16, v98
	v_pk_add_f32 v[98:99], v[138:139], v[154:155]
	v_cmp_gt_u32_e64 s[46:47], 16, v97
	v_cndmask_b32_e32 v154, v214, v98, vcc
	v_add_u32_e32 v97, 25, v1
	v_add_u32_e32 v98, 24, v1
	v_cndmask_b32_e64 v155, v214, v99, s[46:47]
	v_cmp_gt_u32_e32 vcc, 16, v98
	v_cmp_gt_u32_e64 s[46:47], 16, v97
	v_pk_add_f32 v[98:99], v[140:141], v[156:157]
	v_add_u32_e32 v97, 27, v1
	v_add_u32_e32 v1, 26, v1
	v_cndmask_b32_e32 v156, v214, v98, vcc
	v_cmp_gt_u32_e32 vcc, 16, v1
	v_max_f32_e32 v1, v197, v196
	v_cndmask_b32_e64 v157, v214, v99, s[46:47]
	v_cmp_gt_u32_e64 s[46:47], 16, v97
	v_max3_f32 v97, v146, v147, v14
	v_max3_f32 v1, v1, v96, v15
	v_pk_add_f32 v[98:99], v[142:143], v[144:145]
	v_max3_f32 v1, v1, v206, v148
	v_max3_f32 v97, v97, v150, v151
	v_cndmask_b32_e64 v159, v214, v99, s[46:47]
	v_cndmask_b32_e32 v158, v214, v98, vcc
	v_max3_f32 v1, v1, v149, v152
	v_max3_f32 v97, v97, v154, v155
	v_max3_f32 v1, v1, v153, v156
	v_max3_f32 v97, v97, v158, v159
	v_max3_f32 v1, v1, v157, v207
	v_max3_f32 v97, v97, v209, v103
	v_max3_f32 v1, v1, v208, v97
	v_mov_b32_e32 v97, v1
	s_nop 1
	v_permlane32_swap_b32_e32 v1, v97
	v_max_f32_e32 v1, v1, v97
	v_cmp_lt_f32_e32 vcc, s92, v1
	s_cmp_lg_u64 vcc, 0
	s_cselect_b64 s[6:7], -1, 0
	s_cbranch_vccnz .LBB0_331
	v_mov_b64_e32 v[142:143], v[126:127]
	v_mov_b64_e32 v[140:141], v[124:125]
	v_mov_b64_e32 v[138:139], v[122:123]
	v_mov_b64_e32 v[136:137], v[120:121]
	v_mov_b64_e32 v[134:135], v[118:119]
	v_mov_b64_e32 v[132:133], v[116:117]
	v_mov_b64_e32 v[130:131], v[114:115]
	v_mov_b64_e32 v[128:129], v[112:113]
	v_mov_b32_e32 v1, v240

; __device__ __forceinline__ void na_unit3(char* lds, const bf16_t* __restrict__ Qp, const bf16_t* __restrict__ Knp, const bf16_t* __restrict__ Vp, ...
;     ...
;   if (j < NT) { STEP(pA0, pA1, pB0, pB1, j); }
.LBB0_340:
	s_cmp_ge_i32 s31, s95
	s_cselect_b64 s[6:7], -1, 0
	s_add_i32 s95, s95, 8
	s_cmp_lt_i32 s31, s95
	s_cselect_b64 s[8:9], -1, 0
	s_and_b64 s[6:7], s[6:7], s[8:9]
	s_andn2_b64 vcc, exec, s[6:7]
	s_cbranch_vccnz .LBB0_345
	v_exp_f32_e32 v80, v80
	v_exp_f32_e32 v81, v81
	v_add_u32_e32 v1, s0, v228
	s_nop 0
	v_add_f32_e32 v2, v144, v80
	v_exp_f32_e32 v82, v82
	v_exp_f32_e32 v83, v83
	v_add_f32_e32 v2, v81, v2
	s_nop 0
	v_add_f32_e32 v2, v2, v82
	v_exp_f32_e32 v84, v84
	v_exp_f32_e32 v85, v85
	v_add_f32_e32 v2, v83, v2
	s_nop 0
	v_add_f32_e32 v2, v2, v84
	v_exp_f32_e32 v86, v86
	v_exp_f32_e32 v87, v87
	v_add_f32_e32 v2, v85, v2
	s_nop 0
	v_add_f32_e32 v2, v2, v86
	v_add_f32_e32 v6, v87, v2
	v_cvt_pk_bf16_f32 v2, v80, v81
	v_cvt_pk_bf16_f32 v3, v82, v83
	v_cvt_pk_bf16_f32 v4, v84, v85
	v_cvt_pk_bf16_f32 v5, v86, v87
	s_nop 0
	v_permlane32_swap_b32_e32 v2, v4
	v_permlane32_swap_b32_e32 v3, v5
	v_mov_b32_e32 v7, v6
	s_nop 1
	v_permlane32_swap_b32_e32 v6, v7
	v_add_f32_e32 v6, v6, v7
	v_add_f32_e32 v158, v158, v6
	ds_read_b64_tr_b16 v[6:7], v1
	ds_read_b64_tr_b16 v[8:9], v1 offset:2048
	ds_read_b64_tr_b16 v[10:11], v1 offset:512
	ds_read_b64_tr_b16 v[12:13], v1 offset:2560
	ds_read_b64_tr_b16 v[80:81], v1 offset:1024
	ds_read_b64_tr_b16 v[82:83], v1 offset:3072
	s_waitcnt lgkmcnt(4)
	v_mfma_f32_32x32x16_bf16 v[64:79], v[196:199], v[6:9], v[64:79]
	ds_read_b64_tr_b16 v[84:85], v1 offset:1536
	ds_read_b64_tr_b16 v[86:87], v1 offset:3584
	s_sub_i32 s0, s85, s94
	s_add_i32 s0, s0, s13
	v_lshl_or_b32 v14, v222, 2, s27
	s_mulk_i32 s0, 0x7c
	v_sub_u32_e32 v14, v14, v226
	s_add_i32 s0, s0, 0
	s_add_i32 s0, s0, 0x20c00
	s_waitcnt lgkmcnt(4)
	v_mfma_f32_32x32x16_bf16 v[48:63], v[196:199], v[10:13], v[48:63]
	ds_read_b64_tr_b16 v[96:97], v1 offset:4096
	ds_read_b64_tr_b16 v[98:99], v1 offset:6144
	s_waitcnt lgkmcnt(4)
	v_mfma_f32_32x32x16_bf16 v[32:47], v[196:199], v[80:83], v[32:47]
	ds_read_b64_tr_b16 v[10:11], v1 offset:4608
	ds_read_b64_tr_b16 v[12:13], v1 offset:6656
	s_waitcnt lgkmcnt(4)
	v_mfma_f32_32x32x16_bf16 v[16:31], v[196:199], v[84:87], v[16:31]
	ds_read_b64_tr_b16 v[6:7], v1 offset:5120
	ds_read_b64_tr_b16 v[8:9], v1 offset:7168
	s_nop 0
	v_lshl_add_u32 v94, v14, 2, s0
	ds_read2_b32 v[14:15], v94 offset0:232 offset1:233
	ds_read2_b32 v[80:81], v94 offset0:234 offset1:235
	ds_read2_b32 v[82:83], v94 offset0:240 offset1:241
	ds_read2_b32 v[84:85], v94 offset0:242 offset1:243
	v_add_u32_e32 v90, 0x400, v94
	v_add_u32_e32 v92, 0x408, v94
	v_add_u32_e32 v95, 0x420, v94
	v_add_u32_e32 v100, 0x428, v94
	v_add_u32_e32 v102, 0x440, v94
	v_add_u32_e32 v104, 0x448, v94
	ds_read2_b32 v[86:87], v94 offset0:248 offset1:249
	ds_read2_b32 v[88:89], v94 offset0:250 offset1:251
	ds_read2_b32 v[90:91], v90 offset1:1
	ds_read2_b32 v[92:93], v92 offset1:1
	ds_read2_b32 v[94:95], v95 offset1:1
	ds_read2_b32 v[100:101], v100 offset1:1
	ds_read2_b32 v[102:103], v102 offset1:1
	ds_read2_b32 v[104:105], v104 offset1:1
	s_waitcnt lgkmcnt(11)
	s_waitcnt lgkmcnt(10)
	s_waitcnt lgkmcnt(9)
	v_mov_b32_e32 v14, 0xff800000
	v_mov_b32_e32 v15, 0xff800000
	s_nop 1
	v_permlane32_swap_b32_e32 v14, v15
	v_max_f32_e32 v14, v14, v15
	v_cmp_lt_f32_e32 vcc, s92, v14
	s_cmp_lg_u64 vcc, 0
	s_cselect_b64 s[6:7], -1, 0
	s_waitcnt lgkmcnt(8)
	s_waitcnt lgkmcnt(7)
	s_waitcnt lgkmcnt(6)
	s_waitcnt lgkmcnt(5)
	s_waitcnt lgkmcnt(4)
	s_waitcnt lgkmcnt(3)
	s_waitcnt lgkmcnt(2)
	s_waitcnt lgkmcnt(1)
	s_waitcnt lgkmcnt(0)
	s_cbranch_vccnz .LBB0_349
	v_mov_b32_e32 v82, 0xff800000
